# bundle on v113: attention lane^16/^32 reductions via permlane swaps, P4 epilogue rstd-broadcast v_movs folded into op_sel_hi, SGU LayerNorm reductions interleaved
# baseline (speedup 1.0000x reference)
.LBB0_417:
	s_and_b32 s10, s8, 12
	s_mul_i32 s36, s10, 0xe00
	v_lshl_add_u64 v[72:73], v[38:39], 0, s[36:37]
	v_lshl_add_u64 v[78:79], v[72:73], 0, s[52:53]
	v_lshlrev_b32_e32 v253, 16, v153
	s_waitcnt vmcnt(5)
	v_lshlrev_b32_e32 v67, 16, v156
	s_waitcnt vmcnt(3)
	v_lshlrev_b32_e32 v252, 16, v158
	global_load_ushort v225, v[72:73], off offset:2560 nt
	global_load_ushort v153, v[72:73], off offset:2688 nt
	global_load_ushort v226, v[72:73], off offset:2816 nt
	global_load_ushort v227, v[72:73], off offset:2944 nt
	global_load_ushort v228, v[72:73], off offset:3072 nt
	global_load_ushort v229, v[72:73], off offset:3200 nt
	global_load_ushort v230, v[72:73], off offset:3328 nt
	global_load_ushort v156, v[72:73], off offset:3456 nt
	global_load_ushort v232, v[78:79], off offset:3584 nt
	global_load_ushort v158, v[78:79], off offset:3712 nt
	global_load_ushort v233, v[78:79], off offset:3840 nt
	global_load_ushort v234, v[78:79], off offset:3968 nt
	v_add_co_u32_e32 v78, vcc, s93, v72
	v_lshlrev_b32_e32 v65, 16, v161
	s_nop 0
	v_addc_co_u32_e32 v79, vcc, 0, v73, vcc
	global_load_ushort v235, v[78:79], off offset:2560 nt
	global_load_ushort v236, v[78:79], off offset:2688 nt
	global_load_ushort v237, v[78:79], off offset:2816 nt
	global_load_ushort v161, v[78:79], off offset:2944 nt
	v_add_co_u32_e32 v78, vcc, s94, v72
	v_and_b32_e32 v69, 0xffff0000, v68
	s_nop 0
	v_addc_co_u32_e32 v79, vcc, 0, v73, vcc
	v_add_co_u32_e32 v72, vcc, s95, v72
	v_lshlrev_b32_e32 v68, 16, v68
	s_nop 0
	v_addc_co_u32_e32 v73, vcc, 0, v73, vcc
	s_waitcnt vmcnt(17)
	v_lshlrev_b32_e32 v251, 16, v162
	v_lshlrev_b32_e32 v63, 16, v163
	s_waitcnt vmcnt(16)
	v_lshlrev_b32_e32 v250, 16, v165
	v_lshlrev_b32_e32 v61, 16, v160
	global_load_ushort v238, v[78:79], off offset:1536 nt
	global_load_ushort v162, v[78:79], off offset:1664 nt
	global_load_ushort v239, v[78:79], off offset:1792 nt
	global_load_ushort v240, v[78:79], off offset:1920 nt
	global_load_ushort v241, v[78:79], off offset:2048 nt
	global_load_ushort v242, v[78:79], off offset:2176 nt
	global_load_ushort v243, v[78:79], off offset:2304 nt
	global_load_ushort v163, v[78:79], off offset:2432 nt
	global_load_ushort v244, v[72:73], off offset:1024 nt
	global_load_ushort v165, v[72:73], off offset:1152 nt
	global_load_ushort v245, v[72:73], off offset:1280 nt
	global_load_ushort v246, v[72:73], off offset:1408 nt
	global_load_ushort v247, v[72:73], off offset:1536 nt
	global_load_ushort v248, v[72:73], off offset:1664 nt
	global_load_ushort v249, v[72:73], off offset:1792 nt
	global_load_ushort v160, v[72:73], off offset:1920 nt
	v_add_f32_e32 v71, 0, v69
	v_pk_mul_f32 v[72:73], v[68:69], v[68:69]
	v_add_f32_e32 v71, v71, v253
	v_fma_f32 v73, v253, v253, v73
	v_add_f32_e32 v71, v71, v68
	v_add_f32_e32 v75, v72, v73
	v_and_b32_e32 v73, 0xffff0000, v70
	v_lshlrev_b32_e32 v72, 16, v70
	v_add_f32_e32 v77, v71, v73
	v_pk_mul_f32 v[70:71], v[72:73], v[72:73]
	v_mul_f32_e32 v92, v67, v67
	v_add_f32_e32 v71, v71, v75
	v_add_f32_e32 v75, v77, v72
	v_add_f32_e32 v77, v70, v71
	v_and_b32_e32 v71, 0xffff0000, v66
	v_lshlrev_b32_e32 v70, 16, v66
	v_pk_mul_f32 v[78:79], v[70:71], v[70:71]
	v_add_f32_e32 v66, v75, v71
	v_add_f32_e32 v75, v79, v77
	v_add_f32_e32 v93, v66, v70
	v_add_f32_e32 v66, v78, v75
	v_and_b32_e32 v75, 0xffff0000, v74
	v_lshlrev_b32_e32 v74, 16, v74
	v_add_f32_e32 v77, 0, v75
	v_pk_mul_f32 v[78:79], v[74:75], v[74:75]
	v_add_f32_e32 v77, v77, v252
	v_fma_f32 v79, v252, v252, v79
	v_add_f32_e32 v77, v77, v74
	v_add_f32_e32 v81, v78, v79
	v_and_b32_e32 v79, 0xffff0000, v76
	v_lshlrev_b32_e32 v78, 16, v76
	v_add_f32_e32 v83, v77, v79
	v_pk_mul_f32 v[76:77], v[78:79], v[78:79]
	v_pk_add_f32 v[92:93], v[92:93], v[66:67]
	v_add_f32_e32 v77, v77, v81
	v_add_f32_e32 v81, v83, v78
	v_add_f32_e32 v83, v76, v77
	v_and_b32_e32 v77, 0xffff0000, v64
	v_lshlrev_b32_e32 v76, 16, v64
	v_pk_mul_f32 v[84:85], v[76:77], v[76:77]
	v_add_f32_e32 v64, v81, v77
	v_add_f32_e32 v81, v85, v83
	v_add_f32_e32 v95, v64, v76
	v_add_f32_e32 v64, v84, v81
	v_and_b32_e32 v81, 0xffff0000, v80
	v_lshlrev_b32_e32 v80, 16, v80
	v_add_f32_e32 v83, 0, v81
	v_pk_mul_f32 v[84:85], v[80:81], v[80:81]
	v_add_f32_e32 v83, v83, v251
	v_fma_f32 v85, v251, v251, v85
	v_add_f32_e32 v83, v83, v80
	v_add_f32_e32 v87, v84, v85
	v_and_b32_e32 v85, 0xffff0000, v82
	v_lshlrev_b32_e32 v84, 16, v82
	v_add_f32_e32 v89, v83, v85
	v_pk_mul_f32 v[82:83], v[84:85], v[84:85]
	v_add_f32_e32 v83, v83, v87
	v_add_f32_e32 v87, v89, v84
	v_add_f32_e32 v89, v82, v83
	v_and_b32_e32 v83, 0xffff0000, v62
	v_lshlrev_b32_e32 v82, 16, v62
	v_pk_mul_f32 v[90:91], v[82:83], v[82:83]
	v_add_f32_e32 v62, v87, v83
	v_add_f32_e32 v87, v91, v89
	v_add_f32_e32 v117, v62, v82
	v_add_f32_e32 v62, v90, v87
	v_and_b32_e32 v87, 0xffff0000, v86
	v_lshlrev_b32_e32 v86, 16, v86
	v_add_f32_e32 v89, 0, v87
	v_pk_mul_f32 v[90:91], v[86:87], v[86:87]
	v_add_f32_e32 v89, v89, v250
	v_fma_f32 v91, v250, v250, v91
	v_add_f32_e32 v89, v89, v86
	v_add_f32_e32 v118, v90, v91
	v_and_b32_e32 v91, 0xffff0000, v88
	v_lshlrev_b32_e32 v90, 16, v88
	v_add_f32_e32 v119, v89, v91
	v_pk_mul_f32 v[88:89], v[90:91], v[90:91]
	v_mul_f32_e32 v94, v65, v65
	v_add_f32_e32 v89, v89, v118
	v_add_f32_e32 v118, v119, v90
	v_add_f32_e32 v120, v88, v89
	v_and_b32_e32 v89, 0xffff0000, v60
	v_lshlrev_b32_e32 v88, 16, v60
	v_add_f32_e32 v60, v118, v89
	v_pk_mul_f32 v[118:119], v[88:89], v[88:89]
	v_pk_add_f32 v[94:95], v[94:95], v[64:65]
	v_add_f32_e32 v120, v119, v120
	v_add_f32_e32 v119, v60, v88
	v_add_f32_e32 v60, v118, v120
	v_mul_f32_e32 v116, v63, v63
	v_pk_add_f32 v[116:117], v[116:117], v[62:63]
	v_mul_f32_e32 v118, v61, v61
	v_pk_add_f32 v[118:119], v[118:119], v[60:61]
	ds_bpermute_b32 v187, v154, v93
	ds_bpermute_b32 v186, v154, v92
	ds_bpermute_b32 v189, v154, v95
	ds_bpermute_b32 v188, v154, v94
	ds_bpermute_b32 v191, v154, v117
	ds_bpermute_b32 v190, v154, v116
	ds_bpermute_b32 v193, v154, v119
	ds_bpermute_b32 v192, v154, v118
	s_waitcnt lgkmcnt(0)
	v_pk_add_f32 v[92:93], v[92:93], v[186:187]
	v_pk_add_f32 v[94:95], v[94:95], v[188:189]
	v_pk_add_f32 v[116:117], v[116:117], v[190:191]
	v_pk_add_f32 v[118:119], v[118:119], v[192:193]
	ds_bpermute_b32 v187, v155, v93
	ds_bpermute_b32 v186, v155, v92
	ds_bpermute_b32 v189, v155, v95
	ds_bpermute_b32 v188, v155, v94
	ds_bpermute_b32 v191, v155, v117
	ds_bpermute_b32 v190, v155, v116
	ds_bpermute_b32 v193, v155, v119
	ds_bpermute_b32 v192, v155, v118
	s_waitcnt lgkmcnt(0)
	v_pk_add_f32 v[92:93], v[92:93], v[186:187]
	v_pk_add_f32 v[94:95], v[94:95], v[188:189]
	v_pk_add_f32 v[116:117], v[116:117], v[190:191]
	v_pk_add_f32 v[118:119], v[118:119], v[192:193]
	ds_bpermute_b32 v187, v157, v93
	ds_bpermute_b32 v186, v157, v92
	ds_bpermute_b32 v189, v157, v95
	ds_bpermute_b32 v188, v157, v94
	ds_bpermute_b32 v191, v157, v117
	ds_bpermute_b32 v190, v157, v116
	ds_bpermute_b32 v193, v157, v119
	ds_bpermute_b32 v192, v157, v118
	s_waitcnt lgkmcnt(0)
	v_pk_add_f32 v[92:93], v[92:93], v[186:187]
	v_pk_add_f32 v[94:95], v[94:95], v[188:189]
	v_pk_add_f32 v[116:117], v[116:117], v[190:191]
	v_pk_add_f32 v[118:119], v[118:119], v[192:193]
	ds_bpermute_b32 v187, v159, v93
	ds_bpermute_b32 v186, v159, v92
	ds_bpermute_b32 v189, v159, v95
	ds_bpermute_b32 v188, v159, v94
	ds_bpermute_b32 v191, v159, v117
	ds_bpermute_b32 v190, v159, v116
	ds_bpermute_b32 v193, v159, v119
	ds_bpermute_b32 v192, v159, v118
	s_waitcnt lgkmcnt(0)
	v_pk_add_f32 v[92:93], v[92:93], v[186:187]
	v_pk_add_f32 v[94:95], v[94:95], v[188:189]
	v_pk_add_f32 v[116:117], v[116:117], v[190:191]
	v_pk_add_f32 v[118:119], v[118:119], v[192:193]
	ds_bpermute_b32 v187, v129, v93
	ds_bpermute_b32 v186, v129, v92
	ds_bpermute_b32 v189, v129, v95
	ds_bpermute_b32 v188, v129, v94
	ds_bpermute_b32 v191, v129, v117
	ds_bpermute_b32 v190, v129, v116
	ds_bpermute_b32 v193, v129, v119
	ds_bpermute_b32 v192, v129, v118
	s_waitcnt lgkmcnt(0)
	v_pk_add_f32 v[92:93], v[92:93], v[186:187]
	v_pk_add_f32 v[94:95], v[94:95], v[188:189]
	v_pk_add_f32 v[116:117], v[116:117], v[190:191]
	v_pk_add_f32 v[118:119], v[118:119], v[192:193]
	ds_bpermute_b32 v187, v131, v93
	ds_bpermute_b32 v186, v131, v92
	ds_bpermute_b32 v189, v131, v95
	ds_bpermute_b32 v188, v131, v94
	ds_bpermute_b32 v191, v131, v117
	ds_bpermute_b32 v190, v131, v116
	ds_bpermute_b32 v193, v131, v119
	ds_bpermute_b32 v192, v131, v118
	s_waitcnt lgkmcnt(0)
	v_pk_add_f32 v[92:93], v[92:93], v[186:187]
	v_pk_add_f32 v[94:95], v[94:95], v[188:189]
	v_pk_add_f32 v[116:117], v[116:117], v[190:191]
	v_pk_add_f32 v[118:119], v[118:119], v[192:193]
	s_add_i32 s8, s8, 4
	v_pk_mul_f32 v[92:93], v[92:93], s[54:55] op_sel_hi:[1,0]
	v_fma_f32 v66, -v93, v93, v92
	v_max_f32_e32 v66, 0, v66
	v_add_f32_e32 v66, 0x3727c5ac, v66
	v_rsq_f32_e32 v66, v66
	v_sub_f32_e32 v69, v69, v93
	v_mul_f32_e32 v69, v69, v66
	v_fma_f32 v69, v37, v69, v138
	v_sub_f32_e32 v68, v68, v93
	v_mul_f32_e32 v68, v68, v66
	v_fma_f32 v68, v141, v68, v142
	v_sub_f32_e32 v67, v67, v93
	v_pk_mul_f32 v[94:95], v[94:95], s[54:55] op_sel_hi:[1,0]
	v_fma_f32 v64, -v95, v95, v94
	v_max_f32_e32 v64, 0, v64
	v_add_f32_e32 v64, 0x3727c5ac, v64
	v_rsq_f32_e32 v64, v64
	v_sub_f32_e32 v75, v75, v95
	v_mul_f32_e32 v75, v75, v64
	v_fma_f32 v75, v37, v75, v138
	v_sub_f32_e32 v65, v65, v95
	v_pk_mul_f32 v[116:117], v[116:117], s[54:55] op_sel_hi:[1,0]
	v_fma_f32 v62, -v117, v117, v116
	v_max_f32_e32 v62, 0, v62
	v_add_f32_e32 v62, 0x3727c5ac, v62
	v_rsq_f32_e32 v62, v62
	v_sub_f32_e32 v81, v81, v117
	v_mul_f32_e32 v81, v81, v62
	v_fma_f32 v81, v37, v81, v138
	v_sub_f32_e32 v63, v63, v117
	s_nop 0
	v_pk_mul_f32 v[118:119], v[118:119], s[54:55] op_sel_hi:[1,0]
	v_cvt_pk_bf16_f32 v120, v69, v75
	v_sub_f32_e32 v69, v253, v93
	v_fma_f32 v60, -v119, v119, v118
	v_max_f32_e32 v60, 0, v60
	v_add_f32_e32 v60, 0x3727c5ac, v60
	v_rsq_f32_e32 v60, v60
	v_sub_f32_e32 v87, v87, v119
	v_mul_f32_e32 v69, v69, v66
	v_add_u32_e32 v75, s9, v164
	v_mul_f32_e32 v87, v87, v60
	v_fma_f32 v87, v37, v87, v138
	v_cvt_pk_bf16_f32 v121, v81, v87
	v_sub_f32_e32 v81, v252, v95
	v_fma_f32 v69, v139, v69, v140
	v_mul_f32_e32 v81, v81, v64
	ds_write_b64 v75, v[120:121] offset:32
	v_fma_f32 v81, v139, v81, v140
	v_cvt_pk_bf16_f32 v120, v69, v81
	v_sub_f32_e32 v69, v74, v95
	v_sub_f32_e32 v87, v251, v117
	v_sub_f32_e32 v92, v250, v119
	v_mul_f32_e32 v69, v69, v64
	v_sub_f32_e32 v74, v80, v117
	v_sub_f32_e32 v80, v86, v119
	v_mul_f32_e32 v87, v87, v62
	v_mul_f32_e32 v92, v92, v60
	v_fma_f32 v69, v141, v69, v142
	v_mul_f32_e32 v74, v74, v62
	v_mul_f32_e32 v80, v80, v60
	v_fma_f32 v87, v139, v87, v140
	v_fma_f32 v92, v139, v92, v140
	v_cvt_pk_bf16_f32 v121, v87, v92
	ds_write_b64 v75, v[120:121] offset:17440
	v_fma_f32 v74, v141, v74, v142
	v_fma_f32 v80, v141, v80, v142
	v_cvt_pk_bf16_f32 v68, v68, v69
	v_cvt_pk_bf16_f32 v69, v74, v80
	ds_write_b64 v75, v[68:69] offset:34848
	v_sub_f32_e32 v68, v73, v93
	v_sub_f32_e32 v69, v79, v95
	v_mul_f32_e32 v68, v68, v66
	v_mul_f32_e32 v69, v69, v64
	v_sub_f32_e32 v73, v85, v117
	v_sub_f32_e32 v74, v91, v119
	v_fma_f32 v68, v143, v68, v144
	v_fma_f32 v69, v143, v69, v144
	v_mul_f32_e32 v73, v73, v62
	v_mul_f32_e32 v74, v74, v60
	v_fma_f32 v73, v143, v73, v144
	v_fma_f32 v74, v143, v74, v144
	v_cvt_pk_bf16_f32 v68, v68, v69
	v_cvt_pk_bf16_f32 v69, v73, v74
	ds_write_b64 v75, v[68:69] offset:52256
	v_sub_f32_e32 v68, v72, v93
	v_sub_f32_e32 v69, v78, v95
	v_sub_f32_e32 v72, v84, v117
	v_mul_f32_e32 v68, v68, v66
	v_mul_f32_e32 v69, v69, v64
	v_mul_f32_e32 v72, v72, v62
	v_sub_f32_e32 v73, v90, v119
	v_fma_f32 v68, v145, v68, v146
	v_fma_f32 v69, v145, v69, v146
	v_fma_f32 v72, v145, v72, v146
	v_mul_f32_e32 v73, v73, v60
	v_fma_f32 v73, v145, v73, v146
	v_cvt_pk_bf16_f32 v68, v68, v69
	v_cvt_pk_bf16_f32 v69, v72, v73
	v_add_u32_e32 v72, 0x11020, v75
	ds_write_b64 v72, v[68:69]
	v_sub_f32_e32 v68, v71, v93
	v_sub_f32_e32 v69, v77, v95
	v_sub_f32_e32 v71, v83, v117
	v_mul_f32_e32 v68, v68, v66
	v_mul_f32_e32 v69, v69, v64
	v_mul_f32_e32 v71, v71, v62
	v_sub_f32_e32 v72, v89, v119
	v_fma_f32 v68, v147, v68, v148
	v_fma_f32 v69, v147, v69, v148
	v_fma_f32 v71, v147, v71, v148
	v_mul_f32_e32 v72, v72, v60
	v_fma_f32 v72, v147, v72, v148
	v_cvt_pk_bf16_f32 v68, v68, v69
	v_cvt_pk_bf16_f32 v69, v71, v72
	v_add_u32_e32 v71, 0x15420, v75
	ds_write_b64 v71, v[68:69]
	v_sub_f32_e32 v68, v70, v93
	v_sub_f32_e32 v69, v76, v95
	v_sub_f32_e32 v70, v82, v117
	v_mul_f32_e32 v68, v68, v66
	v_mul_f32_e32 v69, v69, v64
	v_mul_f32_e32 v70, v70, v62
	v_sub_f32_e32 v71, v88, v119
	v_sub_f32_e32 v61, v61, v119
	v_fma_f32 v68, v149, v68, v150
	v_fma_f32 v69, v149, v69, v150
	v_fma_f32 v70, v149, v70, v150
	v_mul_f32_e32 v71, v71, v60
	v_mul_f32_e32 v62, v63, v62
	v_mul_f32_e32 v60, v61, v60
	v_fma_f32 v71, v149, v71, v150
	v_cvt_pk_bf16_f32 v68, v68, v69
	v_cvt_pk_bf16_f32 v69, v70, v71
	v_add_u32_e32 v70, 0x19820, v75
	v_mul_f32_e32 v66, v67, v66
	v_mul_f32_e32 v64, v65, v64
	v_fma_f32 v62, v151, v62, v152
	v_fma_f32 v61, v151, v60, v152
	ds_write_b64 v70, v[68:69]
	v_fma_f32 v66, v151, v66, v152
	v_fma_f32 v64, v151, v64, v152
	v_cvt_pk_bf16_f32 v60, v66, v64
	v_cvt_pk_bf16_f32 v61, v62, v61
	v_add_u32_e32 v62, 0x1dc20, v75
	s_add_i32 s9, s9, 8
	ds_write_b64 v62, v[60:61]
	s_waitcnt vmcnt(1)
	v_perm_b32 v60, v248, v249, s67
	v_perm_b32 v88, v246, v247, s67
	v_perm_b32 v86, v244, v245, s67
	v_perm_b32 v62, v242, v243, s67
	v_perm_b32 v82, v240, v241, s67
	v_perm_b32 v80, v238, v239, s67
	v_perm_b32 v64, v236, v237, s67
	v_perm_b32 v76, v234, v235, s67
	v_perm_b32 v74, v232, v233, s67
	v_perm_b32 v66, v229, v230, s67
	v_perm_b32 v70, v227, v228, s67
	v_perm_b32 v68, v225, v226, s67
	s_cmp_eq_u32 s9, 0
	s_cbranch_scc0 .LBB0_417
	s_add_u32 s8, s16, 0x100
	s_addc_u32 s9, s17, 0
	v_or_b32_e32 v38, s8, v98
	s_add_u32 s8, s16, 0x180
	v_mov_b32_e32 v39, s9
	s_addc_u32 s9, s17, 0
	v_mov_b32_e32 v61, s9
	v_or_b32_e32 v60, s8, v98
	v_lshlrev_b64 v[38:39], 8, v[38:39]
	v_lshlrev_b64 v[60:61], 8, v[60:61]
	v_lshl_add_u64 v[38:39], s[12:13], 0, v[38:39]
	v_lshlrev_b32_e32 v164, 1, v36
	v_mov_b32_e32 v165, v2
	v_lshl_add_u64 v[60:61], s[12:13], 0, v[60:61]
	v_add_u32_e32 v66, 0, v40
	v_lshl_add_u64 v[36:37], v[38:39], 0, v[164:165]
	v_lshl_add_u64 v[60:61], v[60:61], 0, v[164:165]
	v_mad_u32_u24 v67, v98, s96, v66
	global_load_dwordx4 v[92:95], v[36:37], off
	global_load_dwordx4 v[88:91], v[36:37], off offset:64
	global_load_dwordx4 v[84:87], v[36:37], off offset:128
	s_nop 0
	global_load_dwordx4 v[36:39], v[36:37], off offset:192
	s_nop 0
	global_load_dwordx4 v[80:83], v[60:61], off
	global_load_dwordx4 v[76:79], v[60:61], off offset:64
	global_load_dwordx4 v[72:75], v[60:61], off offset:128
	global_load_dwordx4 v[68:71], v[60:61], off offset:192
	global_load_dwordx2 v[162:163], v[58:59], off offset:2048 nt
	global_load_dwordx2 v[160:161], v[58:59], off offset:2080 nt
	global_load_dwordx2 v[158:159], v[58:59], off offset:2112 nt
	global_load_dwordx2 v[156:157], v[58:59], off offset:2144 nt
	global_load_dwordx2 v[154:155], v[58:59], off offset:2176 nt
	global_load_dwordx2 v[152:153], v[58:59], off offset:2208 nt
	global_load_dwordx2 v[150:151], v[58:59], off offset:2240 nt
	global_load_dwordx2 v[148:149], v[58:59], off offset:2272 nt
	global_load_dwordx2 v[146:147], v[58:59], off offset:2304 nt
	global_load_dwordx2 v[144:145], v[58:59], off offset:2336 nt
	global_load_dwordx2 v[142:143], v[58:59], off offset:2368 nt
	global_load_dwordx2 v[140:141], v[58:59], off offset:2400 nt
	global_load_dwordx2 v[138:139], v[58:59], off offset:2432 nt
	global_load_dwordx2 v[120:121], v[58:59], off offset:2464 nt
	global_load_dwordx2 v[118:119], v[58:59], off offset:2496 nt
	global_load_dwordx2 v[116:117], v[58:59], off offset:2528 nt
	s_waitcnt lgkmcnt(0)
	s_barrier
	ds_read_b128 v[58:61], v67
	ds_read_b128 v[62:65], v67 offset:64
	s_waitcnt lgkmcnt(1)
	v_mfma_f32_16x16x32_bf16 v[58:61], v[58:61], v[32:35], 0
	s_add_u32 s8, s16, 0x200
	s_addc_u32 s9, s17, 0
	v_mul_u32_u24_e32 v233, 0x110, v98
	s_waitcnt lgkmcnt(0)
	v_mfma_f32_16x16x32_bf16 v[58:61], v[62:65], v[28:31], v[58:61]
	ds_read_b128 v[62:65], v67 offset:128
	v_add3_u32 v241, 0, v233, v40
	v_fmamk_f32 v3, v3, 0x3b000000, v221
	s_waitcnt lgkmcnt(0)
	v_mfma_f32_16x16x32_bf16 v[58:61], v[62:65], v[24:27], v[58:61]
	ds_read_b128 v[62:65], v67 offset:192
	v_cmp_gt_u32_e32 vcc, 16, v97
	s_waitcnt lgkmcnt(0)
	v_mfma_f32_16x16x32_bf16 v[58:61], v[62:65], v[20:23], v[58:61]
	v_lshlrev_b32_e32 v62, 16, v56
	v_and_b32_e32 v56, 0xffff0000, v56
	s_nop 5
	v_add_f32_e32 v59, v231, v59
	v_mul_f32_e32 v56, v59, v56
	v_lshlrev_b32_e32 v59, 16, v57
	v_add_f32_e32 v60, v231, v60
	v_mul_f32_e32 v59, v60, v59
	v_and_b32_e32 v57, 0xffff0000, v57
	v_add_f32_e32 v60, v231, v61
	v_add_f32_e32 v58, v231, v58
	v_mul_f32_e32 v57, v60, v57
	v_mul_f32_e32 v58, v58, v62
	v_mul_f32_e32 v60, v56, v56
	v_mul_f32_e32 v61, v57, v57
	v_fmac_f32_e32 v60, v58, v58
	v_fmac_f32_e32 v61, v59, v59
	v_cvt_pk_bf16_f32 v226, v58, v56
	v_cvt_pk_bf16_f32 v225, v59, v57
	ds_read_b128 v[56:59], v67 offset:4352
	v_add_f32_e32 v64, v60, v61
	ds_read_b128 v[60:63], v67 offset:4416
	s_waitcnt lgkmcnt(1)
	v_mfma_f32_16x16x32_bf16 v[56:59], v[56:59], v[32:35], 0
	s_waitcnt lgkmcnt(0)
	v_mfma_f32_16x16x32_bf16 v[56:59], v[60:63], v[28:31], v[56:59]
	ds_read_b128 v[60:63], v67 offset:4480
	s_waitcnt lgkmcnt(0)
	v_mfma_f32_16x16x32_bf16 v[56:59], v[60:63], v[24:27], v[56:59]
	ds_read_b128 v[60:63], v67 offset:4544
	s_waitcnt lgkmcnt(0)
	v_mfma_f32_16x16x32_bf16 v[56:59], v[60:63], v[20:23], v[56:59]
	v_lshlrev_b32_e32 v60, 16, v54
	v_and_b32_e32 v54, 0xffff0000, v54
	s_nop 5
	v_add_f32_e32 v57, v231, v57
	v_mul_f32_e32 v54, v57, v54
	v_lshlrev_b32_e32 v57, 16, v55
	v_add_f32_e32 v58, v231, v58
	v_mul_f32_e32 v57, v58, v57
	v_and_b32_e32 v55, 0xffff0000, v55
	v_add_f32_e32 v58, v231, v59
	v_add_f32_e32 v56, v231, v56
	v_mul_f32_e32 v55, v58, v55
	v_mul_f32_e32 v56, v56, v60
	v_mul_f32_e32 v58, v54, v54
	v_mul_f32_e32 v59, v55, v55
	v_fmac_f32_e32 v58, v56, v56
	v_fmac_f32_e32 v59, v57, v57
	v_cvt_pk_bf16_f32 v228, v56, v54
	v_cvt_pk_bf16_f32 v227, v57, v55
	ds_read_b128 v[54:57], v67 offset:8704
	v_add_f32_e32 v58, v58, v59
	v_add_f32_e32 v62, v64, v58
	ds_read_b128 v[58:61], v67 offset:8768
	s_waitcnt lgkmcnt(1)
	v_mfma_f32_16x16x32_bf16 v[54:57], v[54:57], v[32:35], 0
	s_waitcnt lgkmcnt(0)
	v_mfma_f32_16x16x32_bf16 v[54:57], v[58:61], v[28:31], v[54:57]
	ds_read_b128 v[58:61], v67 offset:8832
	s_waitcnt lgkmcnt(0)
	v_mfma_f32_16x16x32_bf16 v[54:57], v[58:61], v[24:27], v[54:57]
	ds_read_b128 v[58:61], v67 offset:8896
	s_waitcnt lgkmcnt(0)
	v_mfma_f32_16x16x32_bf16 v[54:57], v[58:61], v[20:23], v[54:57]
	v_lshlrev_b32_e32 v58, 16, v52
	v_and_b32_e32 v52, 0xffff0000, v52
	s_nop 5
	v_add_f32_e32 v55, v231, v55
	v_mul_f32_e32 v52, v55, v52
	v_lshlrev_b32_e32 v55, 16, v53
	v_add_f32_e32 v56, v231, v56
	v_mul_f32_e32 v55, v56, v55
	v_and_b32_e32 v53, 0xffff0000, v53
	v_add_f32_e32 v56, v231, v57
	v_add_f32_e32 v54, v231, v54
	v_mul_f32_e32 v53, v56, v53
	v_mul_f32_e32 v54, v54, v58
	v_mul_f32_e32 v56, v52, v52
	v_mul_f32_e32 v57, v53, v53
	v_fmac_f32_e32 v56, v54, v54
	v_fmac_f32_e32 v57, v55, v55
	v_add_f32_e32 v56, v56, v57
	v_cvt_pk_bf16_f32 v230, v54, v52
	v_or_b32_e32 v52, 48, v97
	v_add_f32_e32 v234, v62, v56
	v_mad_u32_u24 v56, v52, s96, v66
	v_cvt_pk_bf16_f32 v229, v55, v53
	v_mul_u32_u24_e32 v239, 0x110, v52
	ds_read_b128 v[52:55], v56
	s_waitcnt lgkmcnt(0)
	v_mfma_f32_16x16x32_bf16 v[32:35], v[52:55], v[32:35], 0
	ds_read_b128 v[52:55], v56 offset:64
	v_add3_u32 v242, 0, v239, v40
	s_waitcnt lgkmcnt(0)
	v_mfma_f32_16x16x32_bf16 v[28:31], v[52:55], v[28:31], v[32:35]
	s_nop 3
	ds_read_b128 v[32:35], v56 offset:128
	s_waitcnt lgkmcnt(0)
	v_mfma_f32_16x16x32_bf16 v[24:27], v[32:35], v[24:27], v[28:31]
	s_nop 2
	ds_read_b128 v[28:31], v56 offset:192
	s_waitcnt lgkmcnt(0)
	v_mfma_f32_16x16x32_bf16 v[20:23], v[28:31], v[20:23], v[24:27]
	s_nop 2
	v_lshlrev_b32_e32 v24, 16, v50
	s_nop 3
	v_add_f32_e32 v20, v231, v20
	v_mul_f32_e32 v20, v20, v24
	v_and_b32_e32 v24, 0xffff0000, v50
	v_add_f32_e32 v21, v231, v21
	v_mul_f32_e32 v21, v21, v24
	v_lshlrev_b32_e32 v24, 16, v51
	v_add_f32_e32 v22, v231, v22
	v_mul_f32_e32 v22, v22, v24
	v_and_b32_e32 v24, 0xffff0000, v51
	v_add_f32_e32 v23, v231, v23
	v_mul_f32_e32 v23, v23, v24
	v_mul_f32_e32 v24, v21, v21
	v_fmac_f32_e32 v24, v20, v20
	v_cvt_pk_bf16_f32 v232, v20, v21
	v_mov_b32_e32 v21, s9
	v_or_b32_e32 v20, s8, v98
	v_lshlrev_b64 v[20:21], 8, v[20:21]
	v_lshl_add_u64 v[20:21], s[12:13], 0, v[20:21]
	v_mul_f32_e32 v25, v23, v23
	v_lshl_add_u64 v[20:21], v[20:21], 0, v[164:165]
	v_fmac_f32_e32 v25, v22, v22
	v_cvt_pk_bf16_f32 v231, v22, v23
	global_load_dwordx4 v[64:67], v[20:21], off
	global_load_dwordx4 v[60:63], v[20:21], off offset:64
	global_load_dwordx4 v[56:59], v[20:21], off offset:128
	global_load_dwordx4 v[52:55], v[20:21], off offset:192
	ds_read_b128 v[20:23], v241 offset:17408
	v_add_f32_e32 v24, v24, v25
	v_add_f32_e32 v28, v234, v24
	ds_read_b128 v[24:27], v241 offset:17472
	s_waitcnt lgkmcnt(1)
	v_mfma_f32_16x16x32_bf16 v[20:23], v[20:23], v[16:19], 0
	s_add_u32 s8, s16, 0x280
	s_addc_u32 s9, s17, 0
	s_waitcnt lgkmcnt(0)
	v_mfma_f32_16x16x32_bf16 v[20:23], v[24:27], v[12:15], v[20:23]
	ds_read_b128 v[24:27], v241 offset:17536
	s_waitcnt lgkmcnt(0)
	v_mfma_f32_16x16x32_bf16 v[20:23], v[24:27], v[8:11], v[20:23]
	ds_read_b128 v[24:27], v241 offset:17600
	s_waitcnt lgkmcnt(0)
	v_mfma_f32_16x16x32_bf16 v[20:23], v[24:27], v[4:7], v[20:23]
	v_lshlrev_b32_e32 v24, 16, v48
	s_nop 6
	v_add_f32_e32 v20, v41, v20
	v_mul_f32_e32 v20, v20, v24
	v_and_b32_e32 v24, 0xffff0000, v48
	v_add_f32_e32 v21, v41, v21
	v_mul_f32_e32 v21, v21, v24
	v_lshlrev_b32_e32 v24, 16, v49
	v_add_f32_e32 v22, v41, v22
	v_mul_f32_e32 v22, v22, v24
	v_and_b32_e32 v24, 0xffff0000, v49
	v_add_f32_e32 v23, v41, v23
	v_mul_f32_e32 v23, v23, v24
	v_mul_f32_e32 v24, v21, v21
	v_mul_f32_e32 v25, v23, v23
	v_fmac_f32_e32 v24, v20, v20
	v_fmac_f32_e32 v25, v22, v22
	v_cvt_pk_bf16_f32 v234, v20, v21
	v_cvt_pk_bf16_f32 v233, v22, v23
	ds_read_b128 v[20:23], v241 offset:21760
	v_add_f32_e32 v24, v24, v25
	v_add_f32_e32 v28, v28, v24
	ds_read_b128 v[24:27], v241 offset:21824
	s_waitcnt lgkmcnt(1)
	v_mfma_f32_16x16x32_bf16 v[20:23], v[20:23], v[16:19], 0
	s_waitcnt lgkmcnt(0)
	v_mfma_f32_16x16x32_bf16 v[20:23], v[24:27], v[12:15], v[20:23]
	ds_read_b128 v[24:27], v241 offset:21888
	s_waitcnt lgkmcnt(0)
	v_mfma_f32_16x16x32_bf16 v[20:23], v[24:27], v[8:11], v[20:23]
	ds_read_b128 v[24:27], v241 offset:21952
	s_waitcnt lgkmcnt(0)
	v_mfma_f32_16x16x32_bf16 v[20:23], v[24:27], v[4:7], v[20:23]
	v_lshlrev_b32_e32 v24, 16, v46
	s_nop 6
	v_add_f32_e32 v20, v41, v20
	v_mul_f32_e32 v20, v20, v24
	v_and_b32_e32 v24, 0xffff0000, v46
	v_add_f32_e32 v21, v41, v21
	v_mul_f32_e32 v21, v21, v24
	v_lshlrev_b32_e32 v24, 16, v47
	v_add_f32_e32 v22, v41, v22
	v_mul_f32_e32 v22, v22, v24
	v_and_b32_e32 v24, 0xffff0000, v47
	v_add_f32_e32 v23, v41, v23
	v_mul_f32_e32 v23, v23, v24
	v_mul_f32_e32 v24, v21, v21
	v_mul_f32_e32 v25, v23, v23
	v_fmac_f32_e32 v24, v20, v20
	v_fmac_f32_e32 v25, v22, v22
	v_cvt_pk_bf16_f32 v236, v20, v21
	v_cvt_pk_bf16_f32 v235, v22, v23
	ds_read_b128 v[20:23], v241 offset:26112
	v_add_f32_e32 v24, v24, v25
	v_add_f32_e32 v28, v28, v24
	ds_read_b128 v[24:27], v241 offset:26176
	s_waitcnt lgkmcnt(1)
	v_mfma_f32_16x16x32_bf16 v[20:23], v[20:23], v[16:19], 0
	s_waitcnt lgkmcnt(0)
	v_mfma_f32_16x16x32_bf16 v[20:23], v[24:27], v[12:15], v[20:23]
	ds_read_b128 v[24:27], v241 offset:26240
	s_waitcnt lgkmcnt(0)
	v_mfma_f32_16x16x32_bf16 v[20:23], v[24:27], v[8:11], v[20:23]
	ds_read_b128 v[24:27], v241 offset:26304
	s_waitcnt lgkmcnt(0)
	v_mfma_f32_16x16x32_bf16 v[20:23], v[24:27], v[4:7], v[20:23]
	v_lshlrev_b32_e32 v24, 16, v44
	s_nop 6
	v_add_f32_e32 v20, v41, v20
	v_mul_f32_e32 v20, v20, v24
	v_and_b32_e32 v24, 0xffff0000, v44
	v_add_f32_e32 v21, v41, v21
	v_mul_f32_e32 v21, v21, v24
	v_lshlrev_b32_e32 v24, 16, v45
	v_add_f32_e32 v22, v41, v22
	v_mul_f32_e32 v22, v22, v24
	v_and_b32_e32 v24, 0xffff0000, v45
	v_add_f32_e32 v23, v41, v23
	v_mul_f32_e32 v23, v23, v24
	v_mul_f32_e32 v24, v21, v21
	v_mul_f32_e32 v25, v23, v23
	v_fmac_f32_e32 v24, v20, v20
	v_fmac_f32_e32 v25, v22, v22
	v_cvt_pk_bf16_f32 v238, v20, v21
	v_cvt_pk_bf16_f32 v237, v22, v23
	ds_read_b128 v[20:23], v242 offset:17408
	s_waitcnt lgkmcnt(0)
	v_mfma_f32_16x16x32_bf16 v[16:19], v[20:23], v[16:19], 0
	ds_read_b128 v[20:23], v242 offset:17472
	v_add_f32_e32 v24, v24, v25
	v_add_f32_e32 v24, v28, v24
	s_waitcnt lgkmcnt(0)
	v_mfma_f32_16x16x32_bf16 v[12:15], v[20:23], v[12:15], v[16:19]
	s_nop 2
	ds_read_b128 v[16:19], v242 offset:17536
	s_waitcnt lgkmcnt(0)
	v_mfma_f32_16x16x32_bf16 v[8:11], v[16:19], v[8:11], v[12:15]
	s_nop 2
	ds_read_b128 v[12:15], v242 offset:17600
	s_waitcnt lgkmcnt(0)
	v_mfma_f32_16x16x32_bf16 v[4:7], v[12:15], v[4:7], v[8:11]
	s_nop 2
	v_lshlrev_b32_e32 v8, 16, v42
	s_nop 3
	v_add_f32_e32 v4, v41, v4
	v_mul_f32_e32 v4, v4, v8
	v_and_b32_e32 v8, 0xffff0000, v42
	v_add_f32_e32 v5, v41, v5
	v_mul_f32_e32 v5, v5, v8
	v_lshlrev_b32_e32 v8, 16, v43
	v_add_f32_e32 v6, v41, v6
	v_mul_f32_e32 v6, v6, v8
	v_and_b32_e32 v8, 0xffff0000, v43
	v_add_f32_e32 v7, v41, v7
	v_mul_f32_e32 v7, v7, v8
	v_mul_f32_e32 v8, v5, v5
	v_fmac_f32_e32 v8, v4, v4
	v_cvt_pk_bf16_f32 v240, v4, v5
	v_mov_b32_e32 v5, s9
	v_or_b32_e32 v4, s8, v98
	v_lshlrev_b64 v[4:5], 8, v[4:5]
	v_lshl_add_u64 v[4:5], s[12:13], 0, v[4:5]
	v_mul_f32_e32 v9, v7, v7
	v_lshl_add_u64 v[4:5], v[4:5], 0, v[164:165]
	v_fmac_f32_e32 v9, v6, v6
	v_cvt_pk_bf16_f32 v239, v6, v7
	global_load_dwordx4 v[48:51], v[4:5], off
	global_load_dwordx4 v[44:47], v[4:5], off offset:64
	global_load_dwordx4 v[40:43], v[4:5], off offset:128
	global_load_dwordx4 v[32:35], v[4:5], off offset:192
	ds_read_b128 v[4:7], v241 offset:34816
	v_add_f32_e32 v8, v8, v9
	v_add_f32_e32 v12, v24, v8
	ds_read_b128 v[8:11], v241 offset:34880
	s_waitcnt vmcnt(31) lgkmcnt(1)
	v_mfma_f32_16x16x32_bf16 v[4:7], v[4:7], v[92:95], 0
	s_add_u32 s8, s16, 0x300
	s_addc_u32 s9, s17, 0
	s_waitcnt vmcnt(30) lgkmcnt(0)
	v_mfma_f32_16x16x32_bf16 v[4:7], v[8:11], v[88:91], v[4:7]
	ds_read_b128 v[8:11], v241 offset:34944
	s_waitcnt vmcnt(29) lgkmcnt(0)
	v_mfma_f32_16x16x32_bf16 v[4:7], v[8:11], v[84:87], v[4:7]
	ds_read_b128 v[8:11], v241 offset:35008
	s_waitcnt vmcnt(28) lgkmcnt(0)
	v_mfma_f32_16x16x32_bf16 v[4:7], v[8:11], v[36:39], v[4:7]
	v_lshlrev_b32_e32 v8, 16, v114
	s_nop 6
	v_add_f32_e32 v4, v167, v4
	v_mul_f32_e32 v4, v4, v8
	v_and_b32_e32 v8, 0xffff0000, v114
	v_add_f32_e32 v5, v167, v5
	v_mul_f32_e32 v5, v5, v8
	v_lshlrev_b32_e32 v8, 16, v115
	v_add_f32_e32 v6, v167, v6
	v_mul_f32_e32 v6, v6, v8
	v_and_b32_e32 v8, 0xffff0000, v115
	v_add_f32_e32 v7, v167, v7
	v_mul_f32_e32 v7, v7, v8
	v_mul_f32_e32 v8, v5, v5
	v_mul_f32_e32 v9, v7, v7
	v_fmac_f32_e32 v8, v4, v4
	v_fmac_f32_e32 v9, v6, v6
	v_cvt_pk_bf16_f32 v115, v4, v5
	v_cvt_pk_bf16_f32 v114, v6, v7
	ds_read_b128 v[4:7], v241 offset:39168
	v_add_f32_e32 v8, v8, v9
	v_add_f32_e32 v12, v12, v8
	ds_read_b128 v[8:11], v241 offset:39232
	s_waitcnt lgkmcnt(1)
	v_mfma_f32_16x16x32_bf16 v[4:7], v[4:7], v[92:95], 0
	s_waitcnt lgkmcnt(0)
	v_mfma_f32_16x16x32_bf16 v[4:7], v[8:11], v[88:91], v[4:7]
	ds_read_b128 v[8:11], v241 offset:39296
	s_waitcnt lgkmcnt(0)
	v_mfma_f32_16x16x32_bf16 v[4:7], v[8:11], v[84:87], v[4:7]
	ds_read_b128 v[8:11], v241 offset:39360
	s_waitcnt lgkmcnt(0)
	v_mfma_f32_16x16x32_bf16 v[4:7], v[8:11], v[36:39], v[4:7]
	v_lshlrev_b32_e32 v8, 16, v112
	s_nop 6
	v_add_f32_e32 v4, v167, v4
	v_mul_f32_e32 v4, v4, v8
	v_and_b32_e32 v8, 0xffff0000, v112
	v_add_f32_e32 v5, v167, v5
	v_mul_f32_e32 v5, v5, v8
	v_lshlrev_b32_e32 v8, 16, v113
	v_add_f32_e32 v6, v167, v6
	v_mul_f32_e32 v6, v6, v8
	v_and_b32_e32 v8, 0xffff0000, v113
	v_add_f32_e32 v7, v167, v7
	v_mul_f32_e32 v7, v7, v8
	v_mul_f32_e32 v8, v5, v5
	v_mul_f32_e32 v9, v7, v7
	v_fmac_f32_e32 v8, v4, v4
	v_fmac_f32_e32 v9, v6, v6
	v_cvt_pk_bf16_f32 v113, v4, v5
	v_cvt_pk_bf16_f32 v112, v6, v7
	ds_read_b128 v[4:7], v241 offset:43520
	v_add_f32_e32 v8, v8, v9
	v_add_f32_e32 v12, v12, v8
	ds_read_b128 v[8:11], v241 offset:43584
	s_waitcnt lgkmcnt(1)
	v_mfma_f32_16x16x32_bf16 v[4:7], v[4:7], v[92:95], 0
	s_waitcnt lgkmcnt(0)
	v_mfma_f32_16x16x32_bf16 v[4:7], v[8:11], v[88:91], v[4:7]
	ds_read_b128 v[8:11], v241 offset:43648
	s_waitcnt lgkmcnt(0)
	v_mfma_f32_16x16x32_bf16 v[4:7], v[8:11], v[84:87], v[4:7]
	ds_read_b128 v[8:11], v241 offset:43712
	s_waitcnt lgkmcnt(0)
	v_mfma_f32_16x16x32_bf16 v[4:7], v[8:11], v[36:39], v[4:7]
	v_lshlrev_b32_e32 v8, 16, v110
	s_nop 6
	v_add_f32_e32 v4, v167, v4
	v_mul_f32_e32 v4, v4, v8
	v_and_b32_e32 v8, 0xffff0000, v110
	v_add_f32_e32 v5, v167, v5
	v_mul_f32_e32 v5, v5, v8
	v_lshlrev_b32_e32 v8, 16, v111
	v_add_f32_e32 v6, v167, v6
	v_mul_f32_e32 v6, v6, v8
	v_and_b32_e32 v8, 0xffff0000, v111
	v_add_f32_e32 v7, v167, v7
	v_mul_f32_e32 v7, v7, v8
	v_mul_f32_e32 v8, v5, v5
	v_mul_f32_e32 v9, v7, v7
	v_fmac_f32_e32 v8, v4, v4
	v_fmac_f32_e32 v9, v6, v6
	v_cvt_pk_bf16_f32 v111, v4, v5
	v_cvt_pk_bf16_f32 v110, v6, v7
	ds_read_b128 v[4:7], v242 offset:34816
	v_add_f32_e32 v8, v8, v9
	v_add_f32_e32 v12, v12, v8
	ds_read_b128 v[8:11], v242 offset:34880
	s_waitcnt lgkmcnt(1)
	v_mfma_f32_16x16x32_bf16 v[4:7], v[4:7], v[92:95], 0
	s_waitcnt lgkmcnt(0)
	v_mfma_f32_16x16x32_bf16 v[4:7], v[8:11], v[88:91], v[4:7]
	ds_read_b128 v[8:11], v242 offset:34944
	s_waitcnt lgkmcnt(0)
	v_mfma_f32_16x16x32_bf16 v[4:7], v[8:11], v[84:87], v[4:7]
	ds_read_b128 v[8:11], v242 offset:35008
	s_waitcnt lgkmcnt(0)
	v_mfma_f32_16x16x32_bf16 v[4:7], v[8:11], v[36:39], v[4:7]
	v_lshlrev_b32_e32 v8, 16, v108
	s_nop 6
	v_add_f32_e32 v4, v167, v4
	v_mul_f32_e32 v4, v4, v8
	v_and_b32_e32 v8, 0xffff0000, v108
	v_add_f32_e32 v5, v167, v5
	v_mul_f32_e32 v5, v5, v8
	v_lshlrev_b32_e32 v8, 16, v109
	v_add_f32_e32 v6, v167, v6
	v_mul_f32_e32 v6, v6, v8
	v_and_b32_e32 v8, 0xffff0000, v109
	v_add_f32_e32 v7, v167, v7
	v_mul_f32_e32 v7, v7, v8
	v_mul_f32_e32 v8, v5, v5
	v_fmac_f32_e32 v8, v4, v4
	v_cvt_pk_bf16_f32 v85, v4, v5
	v_mov_b32_e32 v5, s9
	v_or_b32_e32 v4, s8, v98
	v_lshlrev_b64 v[4:5], 8, v[4:5]
	v_mul_f32_e32 v9, v7, v7
	v_lshl_add_u64 v[4:5], s[12:13], 0, v[4:5]
	v_fmac_f32_e32 v9, v6, v6
	v_lshl_add_u64 v[4:5], v[4:5], 0, v[164:165]
	v_add_f32_e32 v13, v8, v9
	v_cvt_pk_bf16_f32 v84, v6, v7
	global_load_dwordx4 v[36:39], v[4:5], off
	global_load_dwordx4 v[24:27], v[4:5], off offset:64
	global_load_dwordx4 v[16:19], v[4:5], off offset:128
	global_load_dwordx4 v[8:11], v[4:5], off offset:192
	ds_read_b128 v[4:7], v241 offset:52224
	v_add_f32_e32 v20, v12, v13
	ds_read_b128 v[12:15], v241 offset:52288
	s_waitcnt vmcnt(31) lgkmcnt(1)
	v_mfma_f32_16x16x32_bf16 v[4:7], v[4:7], v[80:83], 0
	s_add_u32 s8, s16, 0x380
	s_addc_u32 s9, s17, 0
	s_waitcnt vmcnt(30) lgkmcnt(0)
	v_mfma_f32_16x16x32_bf16 v[4:7], v[12:15], v[76:79], v[4:7]
	ds_read_b128 v[12:15], v241 offset:52352
	s_waitcnt vmcnt(29) lgkmcnt(0)
	v_mfma_f32_16x16x32_bf16 v[4:7], v[12:15], v[72:75], v[4:7]
	ds_read_b128 v[12:15], v241 offset:52416
	s_waitcnt vmcnt(28) lgkmcnt(0)
	v_mfma_f32_16x16x32_bf16 v[4:7], v[12:15], v[68:71], v[4:7]
	v_lshlrev_b32_e32 v12, 16, v106
	s_nop 6
	v_add_f32_e32 v4, v166, v4
	v_mul_f32_e32 v4, v4, v12
	v_and_b32_e32 v12, 0xffff0000, v106
	v_add_f32_e32 v5, v166, v5
	v_mul_f32_e32 v5, v5, v12
	v_lshlrev_b32_e32 v12, 16, v107
	v_add_f32_e32 v6, v166, v6
	v_mul_f32_e32 v6, v6, v12
	v_and_b32_e32 v12, 0xffff0000, v107
	v_add_f32_e32 v7, v166, v7
	v_mul_f32_e32 v7, v7, v12
	v_mul_f32_e32 v12, v5, v5
	v_mul_f32_e32 v13, v7, v7
	v_fmac_f32_e32 v12, v4, v4
	v_fmac_f32_e32 v13, v6, v6
	v_cvt_pk_bf16_f32 v87, v4, v5
	v_cvt_pk_bf16_f32 v86, v6, v7
	ds_read_b128 v[4:7], v241 offset:56576
	v_add_f32_e32 v12, v12, v13
	v_add_f32_e32 v20, v20, v12
	ds_read_b128 v[12:15], v241 offset:56640
	s_waitcnt lgkmcnt(1)
	v_mfma_f32_16x16x32_bf16 v[4:7], v[4:7], v[80:83], 0
	s_waitcnt lgkmcnt(0)
	v_mfma_f32_16x16x32_bf16 v[4:7], v[12:15], v[76:79], v[4:7]
	ds_read_b128 v[12:15], v241 offset:56704
	s_waitcnt lgkmcnt(0)
	v_mfma_f32_16x16x32_bf16 v[4:7], v[12:15], v[72:75], v[4:7]
	ds_read_b128 v[12:15], v241 offset:56768
	s_waitcnt lgkmcnt(0)
	v_mfma_f32_16x16x32_bf16 v[4:7], v[12:15], v[68:71], v[4:7]
	v_lshlrev_b32_e32 v12, 16, v104
	s_nop 6
	v_add_f32_e32 v4, v166, v4
	v_mul_f32_e32 v4, v4, v12
	v_and_b32_e32 v12, 0xffff0000, v104
	v_add_f32_e32 v5, v166, v5
	v_mul_f32_e32 v5, v5, v12
	v_lshlrev_b32_e32 v12, 16, v105
	v_add_f32_e32 v6, v166, v6
	v_mul_f32_e32 v6, v6, v12
	v_and_b32_e32 v12, 0xffff0000, v105
	v_add_f32_e32 v7, v166, v7
	v_mul_f32_e32 v7, v7, v12
	v_mul_f32_e32 v12, v5, v5
	v_mul_f32_e32 v13, v7, v7
	v_fmac_f32_e32 v12, v4, v4
	v_fmac_f32_e32 v13, v6, v6
	v_cvt_pk_bf16_f32 v89, v4, v5
	v_cvt_pk_bf16_f32 v88, v6, v7
	ds_read_b128 v[4:7], v241 offset:60928
	v_add_f32_e32 v12, v12, v13
	v_add_f32_e32 v20, v20, v12
	ds_read_b128 v[12:15], v241 offset:60992
	s_waitcnt lgkmcnt(1)
	v_mfma_f32_16x16x32_bf16 v[4:7], v[4:7], v[80:83], 0
	s_waitcnt lgkmcnt(0)
	v_mfma_f32_16x16x32_bf16 v[4:7], v[12:15], v[76:79], v[4:7]
	ds_read_b128 v[12:15], v241 offset:61056
	s_waitcnt lgkmcnt(0)
	v_mfma_f32_16x16x32_bf16 v[4:7], v[12:15], v[72:75], v[4:7]
	ds_read_b128 v[12:15], v241 offset:61120
	s_waitcnt lgkmcnt(0)
	v_mfma_f32_16x16x32_bf16 v[4:7], v[12:15], v[68:71], v[4:7]
	v_lshlrev_b32_e32 v12, 16, v102
	s_nop 6
	v_add_f32_e32 v4, v166, v4
	v_mul_f32_e32 v4, v4, v12
	v_and_b32_e32 v12, 0xffff0000, v102
	v_add_f32_e32 v5, v166, v5
	v_mul_f32_e32 v5, v5, v12
	v_lshlrev_b32_e32 v12, 16, v103
	v_add_f32_e32 v6, v166, v6
	v_mul_f32_e32 v6, v6, v12
	v_and_b32_e32 v12, 0xffff0000, v103
	v_add_f32_e32 v7, v166, v7
	v_mul_f32_e32 v7, v7, v12
	v_mul_f32_e32 v12, v5, v5
	v_mul_f32_e32 v13, v7, v7
	v_fmac_f32_e32 v12, v4, v4
	v_fmac_f32_e32 v13, v6, v6
	v_cvt_pk_bf16_f32 v91, v4, v5
	v_cvt_pk_bf16_f32 v90, v6, v7
	ds_read_b128 v[4:7], v242 offset:52224
	v_add_f32_e32 v12, v12, v13
	v_add_f32_e32 v92, v20, v12
	ds_read_b128 v[12:15], v242 offset:52288
	s_waitcnt lgkmcnt(1)
	v_mfma_f32_16x16x32_bf16 v[4:7], v[4:7], v[80:83], 0
	v_add_u32_e32 v81, 0x12100, v241
	v_add_u32_e32 v83, 0x13200, v241
	s_waitcnt lgkmcnt(0)
	v_mfma_f32_16x16x32_bf16 v[4:7], v[12:15], v[76:79], v[4:7]
	ds_read_b128 v[12:15], v242 offset:52352
	v_add_u32_e32 v79, 0x11000, v241
	s_waitcnt lgkmcnt(0)
	v_mfma_f32_16x16x32_bf16 v[4:7], v[12:15], v[72:75], v[4:7]
	ds_read_b128 v[12:15], v242 offset:52416
	s_waitcnt lgkmcnt(0)
	v_mfma_f32_16x16x32_bf16 v[4:7], v[12:15], v[68:71], v[4:7]
	v_lshlrev_b32_e32 v12, 16, v100
	s_nop 6
	v_add_f32_e32 v4, v166, v4
	v_mul_f32_e32 v4, v4, v12
	v_and_b32_e32 v12, 0xffff0000, v100
	v_add_f32_e32 v5, v166, v5
	v_mul_f32_e32 v5, v5, v12
	v_lshlrev_b32_e32 v12, 16, v101
	v_add_f32_e32 v6, v166, v6
	v_mul_f32_e32 v6, v6, v12
	v_and_b32_e32 v12, 0xffff0000, v101
	v_add_f32_e32 v7, v166, v7
	v_mul_f32_e32 v7, v7, v12
	v_mul_f32_e32 v12, v5, v5
	v_fmac_f32_e32 v12, v4, v4
	v_cvt_pk_bf16_f32 v69, v4, v5
	v_mov_b32_e32 v5, s9
	v_or_b32_e32 v4, s8, v98
	v_mul_f32_e32 v13, v7, v7
	v_lshlrev_b64 v[4:5], 8, v[4:5]
	v_fmac_f32_e32 v13, v6, v6
	v_lshl_add_u64 v[4:5], s[12:13], 0, v[4:5]
	v_add_f32_e32 v70, v12, v13
	v_lshl_add_u64 v[4:5], v[4:5], 0, v[164:165]
	v_cvt_pk_bf16_f32 v68, v6, v7
	global_load_dwordx4 v[28:31], v[4:5], off
	global_load_dwordx4 v[20:23], v[4:5], off offset:64
	global_load_dwordx4 v[12:15], v[4:5], off offset:128
	s_nop 0
	global_load_dwordx4 v[4:7], v[4:5], off offset:192
	v_add_f32_e32 v78, v92, v70
	ds_read_b128 v[70:73], v79
	ds_read_b128 v[74:77], v79 offset:64
	s_waitcnt vmcnt(15) lgkmcnt(1)
	v_mfma_f32_16x16x32_bf16 v[70:73], v[70:73], v[64:67], 0
	s_waitcnt vmcnt(14) lgkmcnt(0)
	v_mfma_f32_16x16x32_bf16 v[70:73], v[74:77], v[60:63], v[70:73]
	ds_read_b128 v[74:77], v79 offset:128
	s_waitcnt vmcnt(13) lgkmcnt(0)
	v_mfma_f32_16x16x32_bf16 v[70:73], v[74:77], v[56:59], v[70:73]
	ds_read_b128 v[74:77], v79 offset:192
	s_waitcnt vmcnt(12) lgkmcnt(0)
	v_mfma_f32_16x16x32_bf16 v[70:73], v[74:77], v[52:55], v[70:73]
	v_lshlrev_b32_e32 v74, 16, v162
	s_nop 6
	v_add_f32_e32 v70, v137, v70
	v_mul_f32_e32 v70, v70, v74
	v_and_b32_e32 v74, 0xffff0000, v162
	v_add_f32_e32 v71, v137, v71
	v_mul_f32_e32 v71, v71, v74
	v_lshlrev_b32_e32 v74, 16, v163
	v_add_f32_e32 v72, v137, v72
	v_mul_f32_e32 v72, v72, v74
	v_and_b32_e32 v74, 0xffff0000, v163
	v_add_f32_e32 v73, v137, v73
	v_mul_f32_e32 v73, v73, v74
	v_mul_f32_e32 v74, v71, v71
	v_mul_f32_e32 v75, v73, v73
	v_fmac_f32_e32 v74, v70, v70
	v_fmac_f32_e32 v75, v72, v72
	v_add_f32_e32 v74, v74, v75
	v_add_f32_e32 v80, v78, v74
	v_cvt_pk_bf16_f32 v71, v70, v71
	v_cvt_pk_bf16_f32 v70, v72, v73
	ds_read_b128 v[72:75], v81
	ds_read_b128 v[76:79], v81 offset:64
	s_waitcnt lgkmcnt(1)
	v_mfma_f32_16x16x32_bf16 v[72:75], v[72:75], v[64:67], 0
	s_waitcnt lgkmcnt(0)
	v_mfma_f32_16x16x32_bf16 v[72:75], v[76:79], v[60:63], v[72:75]
	ds_read_b128 v[76:79], v81 offset:128
	s_waitcnt lgkmcnt(0)
	v_mfma_f32_16x16x32_bf16 v[72:75], v[76:79], v[56:59], v[72:75]
	ds_read_b128 v[76:79], v81 offset:192
	s_waitcnt lgkmcnt(0)
	v_mfma_f32_16x16x32_bf16 v[72:75], v[76:79], v[52:55], v[72:75]
	v_lshlrev_b32_e32 v76, 16, v160
	s_nop 6
	v_add_f32_e32 v72, v137, v72
	v_mul_f32_e32 v72, v72, v76
	v_and_b32_e32 v76, 0xffff0000, v160
	v_add_f32_e32 v73, v137, v73
	v_mul_f32_e32 v73, v73, v76
	v_lshlrev_b32_e32 v76, 16, v161
	v_add_f32_e32 v74, v137, v74
	v_mul_f32_e32 v74, v74, v76
	v_and_b32_e32 v76, 0xffff0000, v161
	v_add_f32_e32 v75, v137, v75
	v_mul_f32_e32 v75, v75, v76
	v_mul_f32_e32 v76, v73, v73
	v_mul_f32_e32 v77, v75, v75
	v_fmac_f32_e32 v76, v72, v72
	v_fmac_f32_e32 v77, v74, v74
	v_add_f32_e32 v76, v76, v77
	v_add_f32_e32 v82, v80, v76
	v_cvt_pk_bf16_f32 v73, v72, v73
	v_cvt_pk_bf16_f32 v72, v74, v75
	ds_read_b128 v[74:77], v83
	ds_read_b128 v[78:81], v83 offset:64
	s_waitcnt lgkmcnt(1)
	v_mfma_f32_16x16x32_bf16 v[74:77], v[74:77], v[64:67], 0
	s_waitcnt lgkmcnt(0)
	v_mfma_f32_16x16x32_bf16 v[74:77], v[78:81], v[60:63], v[74:77]
	ds_read_b128 v[78:81], v83 offset:128
	s_waitcnt lgkmcnt(0)
	v_mfma_f32_16x16x32_bf16 v[74:77], v[78:81], v[56:59], v[74:77]
	ds_read_b128 v[78:81], v83 offset:192
	s_waitcnt lgkmcnt(0)
	v_mfma_f32_16x16x32_bf16 v[74:77], v[78:81], v[52:55], v[74:77]
	v_lshlrev_b32_e32 v78, 16, v158
	v_add_u32_e32 v81, 0x11000, v242
	s_nop 5
	v_add_f32_e32 v74, v137, v74
	v_mul_f32_e32 v74, v74, v78
	v_and_b32_e32 v78, 0xffff0000, v158
	v_add_f32_e32 v75, v137, v75
	v_mul_f32_e32 v75, v75, v78
	v_lshlrev_b32_e32 v78, 16, v159
	v_add_f32_e32 v76, v137, v76
	v_mul_f32_e32 v76, v76, v78
	v_and_b32_e32 v78, 0xffff0000, v159
	v_add_f32_e32 v77, v137, v77
	v_mul_f32_e32 v77, v77, v78
	v_mul_f32_e32 v78, v75, v75
	v_mul_f32_e32 v79, v77, v77
	v_fmac_f32_e32 v78, v74, v74
	v_fmac_f32_e32 v79, v76, v76
	v_add_f32_e32 v78, v78, v79
	v_add_f32_e32 v80, v82, v78
	v_cvt_pk_bf16_f32 v75, v74, v75
	v_cvt_pk_bf16_f32 v74, v76, v77
	ds_read_b128 v[76:79], v81
	s_waitcnt lgkmcnt(0)
	v_mfma_f32_16x16x32_bf16 v[64:67], v[76:79], v[64:67], 0
	ds_read_b128 v[76:79], v81 offset:64
	s_waitcnt lgkmcnt(0)
	v_mfma_f32_16x16x32_bf16 v[60:63], v[76:79], v[60:63], v[64:67]
	s_nop 4
	ds_read_b128 v[64:67], v81 offset:128
	s_waitcnt lgkmcnt(0)
	v_mfma_f32_16x16x32_bf16 v[56:59], v[64:67], v[56:59], v[60:63]
	s_nop 2
	ds_read_b128 v[60:63], v81 offset:192
	v_add_u32_e32 v65, 0x16500, v241
	v_add_u32_e32 v67, 0x17600, v241
	s_waitcnt lgkmcnt(0)
	v_mfma_f32_16x16x32_bf16 v[52:55], v[60:63], v[52:55], v[56:59]
	s_nop 2
	v_lshlrev_b32_e32 v56, 16, v156
	v_add_u32_e32 v63, 0x15400, v241
	s_nop 2
	v_add_f32_e32 v52, v137, v52
	v_mul_f32_e32 v52, v52, v56
	v_and_b32_e32 v56, 0xffff0000, v156
	v_add_f32_e32 v53, v137, v53
	v_mul_f32_e32 v53, v53, v56
	v_lshlrev_b32_e32 v56, 16, v157
	v_add_f32_e32 v54, v137, v54
	v_mul_f32_e32 v54, v54, v56
	v_and_b32_e32 v56, 0xffff0000, v157
	v_add_f32_e32 v55, v137, v55
	v_mul_f32_e32 v55, v55, v56
	v_mul_f32_e32 v56, v53, v53
	v_mul_f32_e32 v57, v55, v55
	v_fmac_f32_e32 v56, v52, v52
	v_fmac_f32_e32 v57, v54, v54
	v_add_f32_e32 v56, v56, v57
	v_add_f32_e32 v62, v80, v56
	v_cvt_pk_bf16_f32 v53, v52, v53
	v_cvt_pk_bf16_f32 v52, v54, v55
	ds_read_b128 v[54:57], v63
	ds_read_b128 v[58:61], v63 offset:64
	s_waitcnt vmcnt(11) lgkmcnt(1)
	v_mfma_f32_16x16x32_bf16 v[54:57], v[54:57], v[48:51], 0
	s_waitcnt vmcnt(10) lgkmcnt(0)
	v_mfma_f32_16x16x32_bf16 v[54:57], v[58:61], v[44:47], v[54:57]
	ds_read_b128 v[58:61], v63 offset:128
	s_waitcnt vmcnt(9) lgkmcnt(0)
	v_mfma_f32_16x16x32_bf16 v[54:57], v[58:61], v[40:43], v[54:57]
	ds_read_b128 v[58:61], v63 offset:192
	s_waitcnt vmcnt(8) lgkmcnt(0)
	v_mfma_f32_16x16x32_bf16 v[54:57], v[58:61], v[32:35], v[54:57]
	v_lshlrev_b32_e32 v58, 16, v154
	s_nop 6
	v_add_f32_e32 v54, v135, v54
	v_mul_f32_e32 v54, v54, v58
	v_and_b32_e32 v58, 0xffff0000, v154
	v_add_f32_e32 v55, v135, v55
	v_mul_f32_e32 v55, v55, v58
	v_lshlrev_b32_e32 v58, 16, v155
	v_add_f32_e32 v56, v135, v56
	v_mul_f32_e32 v56, v56, v58
	v_and_b32_e32 v58, 0xffff0000, v155
	v_add_f32_e32 v57, v135, v57
	v_mul_f32_e32 v57, v57, v58
	v_mul_f32_e32 v58, v55, v55
	v_mul_f32_e32 v59, v57, v57
	v_fmac_f32_e32 v58, v54, v54
	v_fmac_f32_e32 v59, v56, v56
	v_add_f32_e32 v58, v58, v59
	v_add_f32_e32 v64, v62, v58
	v_cvt_pk_bf16_f32 v55, v54, v55
	v_cvt_pk_bf16_f32 v54, v56, v57
	ds_read_b128 v[56:59], v65
	ds_read_b128 v[60:63], v65 offset:64
	s_waitcnt lgkmcnt(1)
	v_mfma_f32_16x16x32_bf16 v[56:59], v[56:59], v[48:51], 0
	s_waitcnt lgkmcnt(0)
	v_mfma_f32_16x16x32_bf16 v[56:59], v[60:63], v[44:47], v[56:59]
	ds_read_b128 v[60:63], v65 offset:128
	s_waitcnt lgkmcnt(0)
	v_mfma_f32_16x16x32_bf16 v[56:59], v[60:63], v[40:43], v[56:59]
	ds_read_b128 v[60:63], v65 offset:192
	s_waitcnt lgkmcnt(0)
	v_mfma_f32_16x16x32_bf16 v[56:59], v[60:63], v[32:35], v[56:59]
	v_lshlrev_b32_e32 v60, 16, v152
	s_nop 6
	v_add_f32_e32 v56, v135, v56
	v_mul_f32_e32 v56, v56, v60
	v_and_b32_e32 v60, 0xffff0000, v152
	v_add_f32_e32 v57, v135, v57
	v_mul_f32_e32 v57, v57, v60
	v_lshlrev_b32_e32 v60, 16, v153
	v_add_f32_e32 v58, v135, v58
	v_mul_f32_e32 v58, v58, v60
	v_and_b32_e32 v60, 0xffff0000, v153
	v_add_f32_e32 v59, v135, v59
	v_mul_f32_e32 v59, v59, v60
	v_mul_f32_e32 v60, v57, v57
	v_mul_f32_e32 v61, v59, v59
	v_fmac_f32_e32 v60, v56, v56
	v_fmac_f32_e32 v61, v58, v58
	v_add_f32_e32 v60, v60, v61
	v_add_f32_e32 v66, v64, v60
	v_cvt_pk_bf16_f32 v57, v56, v57
	v_cvt_pk_bf16_f32 v56, v58, v59
	ds_read_b128 v[58:61], v67
	ds_read_b128 v[62:65], v67 offset:64
	s_waitcnt lgkmcnt(1)
	v_mfma_f32_16x16x32_bf16 v[58:61], v[58:61], v[48:51], 0
	s_waitcnt lgkmcnt(0)
	v_mfma_f32_16x16x32_bf16 v[58:61], v[62:65], v[44:47], v[58:61]
	ds_read_b128 v[62:65], v67 offset:128
	s_waitcnt lgkmcnt(0)
	v_mfma_f32_16x16x32_bf16 v[58:61], v[62:65], v[40:43], v[58:61]
	ds_read_b128 v[62:65], v67 offset:192
	s_waitcnt lgkmcnt(0)
	v_mfma_f32_16x16x32_bf16 v[58:61], v[62:65], v[32:35], v[58:61]
	v_lshlrev_b32_e32 v62, 16, v150
	v_add_u32_e32 v65, 0x15400, v242
	s_nop 5
	v_add_f32_e32 v58, v135, v58
	v_mul_f32_e32 v58, v58, v62
	v_and_b32_e32 v62, 0xffff0000, v150
	v_add_f32_e32 v59, v135, v59
	v_mul_f32_e32 v59, v59, v62
	v_lshlrev_b32_e32 v62, 16, v151
	v_add_f32_e32 v60, v135, v60
	v_mul_f32_e32 v60, v60, v62
	v_and_b32_e32 v62, 0xffff0000, v151
	v_add_f32_e32 v61, v135, v61
	v_mul_f32_e32 v61, v61, v62
	v_mul_f32_e32 v62, v59, v59
	v_mul_f32_e32 v63, v61, v61
	v_fmac_f32_e32 v62, v58, v58
	v_fmac_f32_e32 v63, v60, v60
	v_add_f32_e32 v62, v62, v63
	v_add_f32_e32 v64, v66, v62
	v_cvt_pk_bf16_f32 v59, v58, v59
	v_cvt_pk_bf16_f32 v58, v60, v61
	ds_read_b128 v[60:63], v65
	s_waitcnt lgkmcnt(0)
	v_mfma_f32_16x16x32_bf16 v[48:51], v[60:63], v[48:51], 0
	ds_read_b128 v[60:63], v65 offset:64
	s_waitcnt lgkmcnt(0)
	v_mfma_f32_16x16x32_bf16 v[44:47], v[60:63], v[44:47], v[48:51]
	s_nop 4
	ds_read_b128 v[48:51], v65 offset:128
	s_waitcnt lgkmcnt(0)
	v_mfma_f32_16x16x32_bf16 v[40:43], v[48:51], v[40:43], v[44:47]
	s_nop 2
	ds_read_b128 v[44:47], v65 offset:192
	v_add_u32_e32 v49, 0x1a900, v241
	v_add_u32_e32 v51, 0x1ba00, v241
	s_waitcnt lgkmcnt(0)
	v_mfma_f32_16x16x32_bf16 v[32:35], v[44:47], v[32:35], v[40:43]
	s_nop 2
	v_lshlrev_b32_e32 v40, 16, v148
	s_nop 3
	v_add_f32_e32 v32, v135, v32
	v_mul_f32_e32 v32, v32, v40
	v_and_b32_e32 v40, 0xffff0000, v148
	v_add_f32_e32 v33, v135, v33
	v_mul_f32_e32 v33, v33, v40
	v_lshlrev_b32_e32 v40, 16, v149
	v_add_f32_e32 v34, v135, v34
	v_mul_f32_e32 v34, v34, v40
	v_and_b32_e32 v40, 0xffff0000, v149
	v_add_f32_e32 v35, v135, v35
	v_mul_f32_e32 v35, v35, v40
	v_mul_f32_e32 v40, v33, v33
	v_mul_f32_e32 v41, v35, v35
	v_fmac_f32_e32 v40, v32, v32
	v_fmac_f32_e32 v41, v34, v34
	v_add_f32_e32 v40, v40, v41
	v_cvt_pk_bf16_f32 v33, v32, v33
	v_cvt_pk_bf16_f32 v32, v34, v35
	v_add_u32_e32 v34, 0x19800, v241
	v_add_f32_e32 v48, v64, v40
	ds_read_b128 v[40:43], v34
	ds_read_b128 v[44:47], v34 offset:64
	s_waitcnt vmcnt(7) lgkmcnt(1)
	v_mfma_f32_16x16x32_bf16 v[40:43], v[40:43], v[36:39], 0
	s_waitcnt vmcnt(6) lgkmcnt(0)
	v_mfma_f32_16x16x32_bf16 v[40:43], v[44:47], v[24:27], v[40:43]
	ds_read_b128 v[44:47], v34 offset:128
	s_waitcnt vmcnt(5) lgkmcnt(0)
	v_mfma_f32_16x16x32_bf16 v[40:43], v[44:47], v[16:19], v[40:43]
	ds_read_b128 v[44:47], v34 offset:192
	v_lshlrev_b32_e32 v34, 16, v146
	s_waitcnt vmcnt(4) lgkmcnt(0)
	v_mfma_f32_16x16x32_bf16 v[40:43], v[44:47], v[8:11], v[40:43]
	s_nop 7
	v_add_f32_e32 v35, v133, v40
	v_mul_f32_e32 v34, v35, v34
	v_and_b32_e32 v35, 0xffff0000, v146
	v_add_f32_e32 v40, v133, v41
	v_mul_f32_e32 v35, v40, v35
	v_lshlrev_b32_e32 v40, 16, v147
	v_add_f32_e32 v41, v133, v42
	v_mul_f32_e32 v40, v41, v40
	v_and_b32_e32 v41, 0xffff0000, v147
	v_add_f32_e32 v42, v133, v43
	v_mul_f32_e32 v41, v42, v41
	v_mul_f32_e32 v42, v35, v35
	v_mul_f32_e32 v43, v41, v41
	v_fmac_f32_e32 v42, v34, v34
	v_fmac_f32_e32 v43, v40, v40
	v_add_f32_e32 v42, v42, v43
	v_add_f32_e32 v48, v48, v42
	v_cvt_pk_bf16_f32 v35, v34, v35
	v_cvt_pk_bf16_f32 v34, v40, v41
	ds_read_b128 v[40:43], v49
	ds_read_b128 v[44:47], v49 offset:64
	s_waitcnt lgkmcnt(1)
	v_mfma_f32_16x16x32_bf16 v[40:43], v[40:43], v[36:39], 0
	s_waitcnt lgkmcnt(0)
	v_mfma_f32_16x16x32_bf16 v[40:43], v[44:47], v[24:27], v[40:43]
	ds_read_b128 v[44:47], v49 offset:128
	s_waitcnt lgkmcnt(0)
	v_mfma_f32_16x16x32_bf16 v[40:43], v[44:47], v[16:19], v[40:43]
	ds_read_b128 v[44:47], v49 offset:192
	s_waitcnt lgkmcnt(0)
	v_mfma_f32_16x16x32_bf16 v[40:43], v[44:47], v[8:11], v[40:43]
	v_lshlrev_b32_e32 v44, 16, v144
	s_nop 6
	v_add_f32_e32 v40, v133, v40
	v_mul_f32_e32 v40, v40, v44
	v_and_b32_e32 v44, 0xffff0000, v144
	v_add_f32_e32 v41, v133, v41
	v_mul_f32_e32 v41, v41, v44
	v_lshlrev_b32_e32 v44, 16, v145
	v_add_f32_e32 v42, v133, v42
	v_mul_f32_e32 v42, v42, v44
	v_and_b32_e32 v44, 0xffff0000, v145
	v_add_f32_e32 v43, v133, v43
	v_mul_f32_e32 v43, v43, v44
	v_mul_f32_e32 v44, v41, v41
	v_mul_f32_e32 v45, v43, v43
	v_fmac_f32_e32 v44, v40, v40
	v_fmac_f32_e32 v45, v42, v42
	v_add_f32_e32 v44, v44, v45
	v_add_f32_e32 v50, v48, v44
	v_cvt_pk_bf16_f32 v41, v40, v41
	v_cvt_pk_bf16_f32 v40, v42, v43
	ds_read_b128 v[42:45], v51
	ds_read_b128 v[46:49], v51 offset:64
	s_waitcnt lgkmcnt(1)
	v_mfma_f32_16x16x32_bf16 v[42:45], v[42:45], v[36:39], 0
	s_waitcnt lgkmcnt(0)
	v_mfma_f32_16x16x32_bf16 v[42:45], v[46:49], v[24:27], v[42:45]
	ds_read_b128 v[46:49], v51 offset:128
	s_waitcnt lgkmcnt(0)
	v_mfma_f32_16x16x32_bf16 v[42:45], v[46:49], v[16:19], v[42:45]
	ds_read_b128 v[46:49], v51 offset:192
	s_waitcnt lgkmcnt(0)
	v_mfma_f32_16x16x32_bf16 v[42:45], v[46:49], v[8:11], v[42:45]
	v_lshlrev_b32_e32 v46, 16, v142
	v_add_u32_e32 v49, 0x19800, v242
	s_nop 5
	v_add_f32_e32 v42, v133, v42
	v_mul_f32_e32 v42, v42, v46
	v_and_b32_e32 v46, 0xffff0000, v142
	v_add_f32_e32 v43, v133, v43
	v_mul_f32_e32 v43, v43, v46
	v_lshlrev_b32_e32 v46, 16, v143
	v_add_f32_e32 v44, v133, v44
	v_mul_f32_e32 v44, v44, v46
	v_and_b32_e32 v46, 0xffff0000, v143
	v_add_f32_e32 v45, v133, v45
	v_mul_f32_e32 v45, v45, v46
	v_mul_f32_e32 v46, v43, v43
	v_mul_f32_e32 v47, v45, v45
	v_fmac_f32_e32 v46, v42, v42
	v_fmac_f32_e32 v47, v44, v44
	v_add_f32_e32 v46, v46, v47
	v_add_f32_e32 v48, v50, v46
	v_cvt_pk_bf16_f32 v43, v42, v43
	v_cvt_pk_bf16_f32 v42, v44, v45
	ds_read_b128 v[44:47], v49
	s_waitcnt lgkmcnt(0)
	v_mfma_f32_16x16x32_bf16 v[36:39], v[44:47], v[36:39], 0
	ds_read_b128 v[44:47], v49 offset:64
	s_waitcnt lgkmcnt(0)
	v_mfma_f32_16x16x32_bf16 v[24:27], v[44:47], v[24:27], v[36:39]
	s_nop 4
	ds_read_b128 v[36:39], v49 offset:128
	s_waitcnt lgkmcnt(0)
	v_mfma_f32_16x16x32_bf16 v[16:19], v[36:39], v[16:19], v[24:27]
	s_nop 2
	ds_read_b128 v[24:27], v49 offset:192
	v_add_u32_e32 v37, 0x1ed00, v241
	s_waitcnt lgkmcnt(0)
	v_mfma_f32_16x16x32_bf16 v[8:11], v[24:27], v[8:11], v[16:19]
	s_nop 2
	v_lshlrev_b32_e32 v16, 16, v140
	s_nop 3
	v_add_f32_e32 v8, v133, v8
	v_mul_f32_e32 v8, v8, v16
	v_and_b32_e32 v16, 0xffff0000, v140
	v_add_f32_e32 v9, v133, v9
	v_mul_f32_e32 v9, v9, v16
	v_lshlrev_b32_e32 v16, 16, v141
	v_add_f32_e32 v10, v133, v10
	v_mul_f32_e32 v10, v10, v16
	v_and_b32_e32 v16, 0xffff0000, v141
	v_add_f32_e32 v11, v133, v11
	v_mul_f32_e32 v11, v11, v16
	v_mul_f32_e32 v16, v9, v9
	v_mul_f32_e32 v17, v11, v11
	v_fmac_f32_e32 v16, v8, v8
	v_fmac_f32_e32 v17, v10, v10
	v_add_f32_e32 v16, v16, v17
	v_cvt_pk_bf16_f32 v9, v8, v9
	v_cvt_pk_bf16_f32 v8, v10, v11
	v_add_u32_e32 v10, 0x1dc00, v241
	v_add_f32_e32 v36, v48, v16
	ds_read_b128 v[16:19], v10
	ds_read_b128 v[24:27], v10 offset:64
	s_waitcnt vmcnt(3) lgkmcnt(1)
	v_mfma_f32_16x16x32_bf16 v[16:19], v[16:19], v[28:31], 0
	s_waitcnt vmcnt(2) lgkmcnt(0)
	v_mfma_f32_16x16x32_bf16 v[16:19], v[24:27], v[20:23], v[16:19]
	ds_read_b128 v[24:27], v10 offset:128
	s_waitcnt vmcnt(1) lgkmcnt(0)
	v_mfma_f32_16x16x32_bf16 v[16:19], v[24:27], v[12:15], v[16:19]
	ds_read_b128 v[24:27], v10 offset:192
	v_lshlrev_b32_e32 v10, 16, v138
	s_waitcnt vmcnt(0) lgkmcnt(0)
	v_mfma_f32_16x16x32_bf16 v[16:19], v[24:27], v[4:7], v[16:19]
	s_nop 7
	v_add_f32_e32 v11, v99, v16
	v_mul_f32_e32 v10, v11, v10
	v_and_b32_e32 v11, 0xffff0000, v138
	v_add_f32_e32 v16, v99, v17
	v_mul_f32_e32 v11, v16, v11
	v_lshlrev_b32_e32 v16, 16, v139
	v_add_f32_e32 v17, v99, v18
	v_mul_f32_e32 v16, v17, v16
	v_and_b32_e32 v17, 0xffff0000, v139
	v_add_f32_e32 v18, v99, v19
	v_mul_f32_e32 v17, v18, v17
	v_mul_f32_e32 v18, v11, v11
	v_mul_f32_e32 v19, v17, v17
	v_fmac_f32_e32 v18, v10, v10
	v_fmac_f32_e32 v19, v16, v16
	v_add_f32_e32 v18, v18, v19
	v_add_f32_e32 v36, v36, v18
	v_cvt_pk_bf16_f32 v11, v10, v11
	v_cvt_pk_bf16_f32 v10, v16, v17
	ds_read_b128 v[16:19], v37
	ds_read_b128 v[24:27], v37 offset:64
	s_waitcnt lgkmcnt(1)
	v_mfma_f32_16x16x32_bf16 v[16:19], v[16:19], v[28:31], 0
	s_waitcnt lgkmcnt(0)
	v_mfma_f32_16x16x32_bf16 v[16:19], v[24:27], v[20:23], v[16:19]
	ds_read_b128 v[24:27], v37 offset:128
	s_waitcnt lgkmcnt(0)
	v_mfma_f32_16x16x32_bf16 v[16:19], v[24:27], v[12:15], v[16:19]
	ds_read_b128 v[24:27], v37 offset:192
	s_waitcnt lgkmcnt(0)
	v_mfma_f32_16x16x32_bf16 v[16:19], v[24:27], v[4:7], v[16:19]
	v_lshlrev_b32_e32 v24, 16, v120
	s_nop 6
	v_add_f32_e32 v16, v99, v16
	v_mul_f32_e32 v16, v16, v24
	v_and_b32_e32 v24, 0xffff0000, v120
	v_add_f32_e32 v17, v99, v17
	v_mul_f32_e32 v17, v17, v24
	v_lshlrev_b32_e32 v24, 16, v121
	v_add_f32_e32 v18, v99, v18
	v_mul_f32_e32 v18, v18, v24
	v_and_b32_e32 v24, 0xffff0000, v121
	v_add_f32_e32 v19, v99, v19
	v_mul_f32_e32 v19, v19, v24
	v_mul_f32_e32 v24, v17, v17
	v_mul_f32_e32 v25, v19, v19
	v_fmac_f32_e32 v24, v16, v16
	v_fmac_f32_e32 v25, v18, v18
	v_add_f32_e32 v24, v24, v25
	v_cvt_pk_bf16_f32 v17, v16, v17
	v_cvt_pk_bf16_f32 v16, v18, v19
	v_add_u32_e32 v18, 0x1fe00, v241
	v_add_f32_e32 v44, v36, v24
	ds_read_b128 v[24:27], v18
	ds_read_b128 v[36:39], v18 offset:64
	s_waitcnt lgkmcnt(1)
	v_mfma_f32_16x16x32_bf16 v[24:27], v[24:27], v[28:31], 0
	s_waitcnt lgkmcnt(0)
	v_mfma_f32_16x16x32_bf16 v[24:27], v[36:39], v[20:23], v[24:27]
	ds_read_b128 v[36:39], v18 offset:128
	s_waitcnt lgkmcnt(0)
	v_mfma_f32_16x16x32_bf16 v[24:27], v[36:39], v[12:15], v[24:27]
	ds_read_b128 v[36:39], v18 offset:192
	v_lshlrev_b32_e32 v18, 16, v118
	s_waitcnt lgkmcnt(0)
	v_mfma_f32_16x16x32_bf16 v[24:27], v[36:39], v[4:7], v[24:27]
	v_add_u32_e32 v37, 0x1dc00, v242
	s_nop 6
	v_add_f32_e32 v19, v99, v24
	v_mul_f32_e32 v18, v19, v18
	v_and_b32_e32 v19, 0xffff0000, v118
	v_add_f32_e32 v24, v99, v25
	v_mul_f32_e32 v19, v24, v19
	v_lshlrev_b32_e32 v24, 16, v119
	v_add_f32_e32 v25, v99, v26
	v_mul_f32_e32 v24, v25, v24
	v_and_b32_e32 v25, 0xffff0000, v119
	v_add_f32_e32 v26, v99, v27
	v_mul_f32_e32 v25, v26, v25
	v_mul_f32_e32 v26, v19, v19
	v_mul_f32_e32 v27, v25, v25
	v_fmac_f32_e32 v26, v18, v18
	v_fmac_f32_e32 v27, v24, v24
	v_add_f32_e32 v26, v26, v27
	v_add_f32_e32 v36, v44, v26
	v_cvt_pk_bf16_f32 v19, v18, v19
	v_cvt_pk_bf16_f32 v18, v24, v25
	ds_read_b128 v[24:27], v37
	s_waitcnt lgkmcnt(0)
	v_mfma_f32_16x16x32_bf16 v[24:27], v[24:27], v[28:31], 0
	ds_read_b128 v[28:31], v37 offset:64
	s_waitcnt lgkmcnt(0)
	v_mfma_f32_16x16x32_bf16 v[20:23], v[28:31], v[20:23], v[24:27]
	s_nop 4
	ds_read_b128 v[24:27], v37 offset:128
	s_waitcnt lgkmcnt(0)
	v_mfma_f32_16x16x32_bf16 v[12:15], v[24:27], v[12:15], v[20:23]
	s_nop 2
	ds_read_b128 v[20:23], v37 offset:192
	s_waitcnt lgkmcnt(0)
	v_mfma_f32_16x16x32_bf16 v[4:7], v[20:23], v[4:7], v[12:15]
	s_nop 2
	v_lshlrev_b32_e32 v12, 16, v116
	s_nop 3
	v_add_f32_e32 v4, v99, v4
	v_mul_f32_e32 v4, v4, v12
	v_and_b32_e32 v12, 0xffff0000, v116
	v_add_f32_e32 v5, v99, v5
	v_mul_f32_e32 v5, v5, v12
	v_lshlrev_b32_e32 v12, 16, v117
	v_add_f32_e32 v6, v99, v6
	v_mul_f32_e32 v6, v6, v12
	v_and_b32_e32 v12, 0xffff0000, v117
	v_add_f32_e32 v7, v99, v7
	v_mul_f32_e32 v7, v7, v12
	v_mul_f32_e32 v12, v5, v5
	v_mul_f32_e32 v13, v7, v7
	v_fmac_f32_e32 v12, v4, v4
	v_fmac_f32_e32 v13, v6, v6
	v_add_f32_e32 v12, v12, v13
	v_add_f32_e32 v12, v36, v12
	v_cvt_pk_bf16_f32 v5, v4, v5
	v_cvt_pk_bf16_f32 v4, v6, v7
	ds_bpermute_b32 v6, v129, v12
	s_waitcnt lgkmcnt(0)
	v_add_f32_e32 v6, v12, v6
	ds_bpermute_b32 v7, v131, v6
	s_and_saveexec_b64 s[8:9], vcc
	s_cbranch_execz .LBB0_368
	v_rsq_f32_e32 v14, v3
	v_lshl_add_u64 v[12:13], v[0:1], 2, s[6:7]
	v_add_co_u32_e32 v12, vcc, 0x1a00000, v12
	s_nop 1
	v_addc_co_u32_e32 v13, vcc, 0, v13, vcc
	global_store_dword v[12:13], v14, off
	s_branch .LBB0_368

.LBB0_583:
	s_or_b64 exec, exec, s[52:53]
	v_fmamk_f32 v156, v166, 0x3a800000, v210
	v_rsq_f32_e32 v166, v156
	v_pk_mul_f32 v[156:157], v[130:131], v[200:201]
	v_pk_mul_f32 v[158:159], v[128:129], v[202:203]
	v_pk_fma_f32 v[156:157], v[122:123], v[162:163], v[156:157]
	v_pk_mul_f32 v[144:145], v[144:145], v[166:167] op_sel_hi:[1,0]
	v_pk_mul_f32 v[146:147], v[146:147], v[166:167] op_sel_hi:[1,0]
	v_pk_fma_f32 v[158:159], v[120:121], v[160:161], v[158:159]
	v_pk_fma_f32 v[156:157], v[118:119], v[146:147], v[156:157]
	v_pk_fma_f32 v[158:159], v[116:117], v[144:145], v[158:159]
	v_pk_add_f32 v[156:157], v[126:127], v[156:157]
	v_pk_add_f32 v[158:159], v[124:125], v[158:159]
	v_pk_mul_f32 v[162:163], v[156:157], v[156:157]
	v_pk_mul_f32 v[168:169], v[158:159], v[158:159]
	v_mov_b64_e32 v[170:171], s[42:43]
	v_pk_fma_f32 v[168:169], v[168:169], s[40:41], v[170:171] op_sel_hi:[1,0,0] neg_lo:[1,0,0] neg_hi:[1,0,0]
	v_pk_fma_f32 v[162:163], v[162:163], s[40:41], v[170:171] op_sel_hi:[1,0,0] neg_lo:[1,0,0] neg_hi:[1,0,0]
	v_pk_mul_f32 v[168:169], v[158:159], v[168:169]
	v_pk_mul_f32 v[162:163], v[156:157], v[162:163]
	v_exp_f32_e32 v168, v168
	v_exp_f32_e32 v169, v169
	v_exp_f32_e32 v162, v162
	v_exp_f32_e32 v163, v163
	v_pk_add_f32 v[168:169], v[168:169], 1.0 op_sel_hi:[1,0]
	v_pk_add_f32 v[162:163], v[162:163], 1.0 op_sel_hi:[1,0]
	v_rcp_f32_e32 v168, v168
	v_rcp_f32_e32 v162, v162
	v_rcp_f32_e32 v163, v163
	v_rcp_f32_e32 v169, v169
	v_pk_mul_f32 v[138:139], v[138:139], v[194:195] op_sel_hi:[1,0]
	v_pk_mul_f32 v[136:137], v[136:137], v[194:195] op_sel_hi:[1,0]
	v_pk_mul_f32 v[156:157], v[156:157], v[162:163]
	v_pk_mul_f32 v[158:159], v[158:159], v[168:169]
	v_pk_mul_f32 v[138:139], v[138:139], v[156:157]
	v_pk_mul_f32 v[136:137], v[136:137], v[158:159]
	v_pk_mul_f32 v[156:157], v[128:129], v[144:145]
	v_cvt_pk_bf16_f32 v136, v136, v137
	v_cvt_pk_bf16_f32 v137, v138, v139
	v_pk_mul_f32 v[138:139], v[130:131], v[146:147]
	v_pk_fma_f32 v[156:157], v[120:121], v[202:203], v[156:157]
	v_pk_fma_f32 v[138:139], v[122:123], v[200:201], v[138:139]
	v_pk_fma_f32 v[156:157], v[116:117], v[152:153], v[156:157]
	v_pk_fma_f32 v[138:139], v[118:119], v[154:155], v[138:139]
	v_pk_add_f32 v[156:157], v[124:125], v[156:157]
	v_pk_add_f32 v[138:139], v[126:127], v[138:139]
	v_pk_mul_f32 v[162:163], v[156:157], v[156:157]
	v_pk_mul_f32 v[158:159], v[138:139], v[138:139]
	v_pk_fma_f32 v[162:163], v[162:163], s[40:41], v[170:171] op_sel_hi:[1,0,0] neg_lo:[1,0,0] neg_hi:[1,0,0]
	v_pk_fma_f32 v[158:159], v[158:159], s[40:41], v[170:171] op_sel_hi:[1,0,0] neg_lo:[1,0,0] neg_hi:[1,0,0]
	v_pk_mul_f32 v[162:163], v[156:157], v[162:163]
	v_pk_mul_f32 v[158:159], v[138:139], v[158:159]
	v_exp_f32_e32 v162, v162
	v_exp_f32_e32 v163, v163
	v_exp_f32_e32 v158, v158
	v_exp_f32_e32 v159, v159
	v_pk_mul_f32 v[132:133], v[132:133], v[166:167] op_sel_hi:[1,0]
	v_pk_add_f32 v[162:163], v[162:163], 1.0 op_sel_hi:[1,0]
	v_pk_mul_f32 v[134:135], v[134:135], v[166:167] op_sel_hi:[1,0]
	v_pk_add_f32 v[158:159], v[158:159], 1.0 op_sel_hi:[1,0]
	v_rcp_f32_e32 v162, v162
	v_rcp_f32_e32 v163, v163
	v_rcp_f32_e32 v158, v158
	v_rcp_f32_e32 v159, v159
	v_pk_mul_f32 v[156:157], v[156:157], v[162:163]
	s_add_i32 s54, s47, 3
	v_pk_mul_f32 v[138:139], v[138:139], v[158:159]
	v_pk_mul_f32 v[132:133], v[132:133], v[156:157]
	v_pk_mul_f32 v[134:135], v[134:135], v[138:139]
	v_cvt_pk_bf16_f32 v132, v132, v133
	v_pk_mul_f32 v[138:139], v[128:129], v[152:153]
	v_cvt_pk_bf16_f32 v133, v134, v135
	v_pk_mul_f32 v[134:135], v[130:131], v[154:155]
	v_pk_fma_f32 v[138:139], v[120:121], v[144:145], v[138:139]
	v_pk_fma_f32 v[134:135], v[122:123], v[146:147], v[134:135]
	v_pk_fma_f32 v[138:139], v[116:117], v[150:151], v[138:139]
	v_pk_fma_f32 v[134:135], v[118:119], v[198:199], v[134:135]
	v_pk_add_f32 v[144:145], v[124:125], v[138:139]
	v_pk_add_f32 v[146:147], v[126:127], v[134:135]
	v_pk_mul_f32 v[150:151], v[144:145], v[144:145]
	v_pk_mul_f32 v[134:135], v[146:147], v[146:147]
	v_pk_fma_f32 v[150:151], v[150:151], s[40:41], v[170:171] op_sel_hi:[1,0,0] neg_lo:[1,0,0] neg_hi:[1,0,0]
	v_pk_fma_f32 v[134:135], v[134:135], s[40:41], v[170:171] op_sel_hi:[1,0,0] neg_lo:[1,0,0] neg_hi:[1,0,0]
	v_pk_mul_f32 v[150:151], v[144:145], v[150:151]
	v_pk_mul_f32 v[134:135], v[146:147], v[134:135]
	v_exp_f32_e32 v150, v150
	v_exp_f32_e32 v151, v151
	v_exp_f32_e32 v134, v134
	v_exp_f32_e32 v135, v135
	v_pk_add_f32 v[150:151], v[150:151], 1.0 op_sel_hi:[1,0]
	v_pk_add_f32 v[134:135], v[134:135], 1.0 op_sel_hi:[1,0]
	v_rcp_f32_e32 v150, v150
	v_rcp_f32_e32 v134, v134
	v_rcp_f32_e32 v135, v135
	v_rcp_f32_e32 v151, v151
	v_pk_mul_f32 v[158:159], v[114:115], v[164:165] op_sel_hi:[1,0]
	v_pk_mul_f32 v[156:157], v[112:113], v[164:165] op_sel_hi:[1,0]
	v_pk_mul_f32 v[112:113], v[146:147], v[134:135]
	v_pk_mul_f32 v[114:115], v[144:145], v[150:151]
	s_mul_hi_i32 s47, s54, 0x2c00
	s_mulk_i32 s54, 0x2c00
	v_pk_mul_f32 v[134:135], v[158:159], v[112:113]
	v_pk_mul_f32 v[112:113], v[156:157], v[114:115]
	s_nop 0
	v_cvt_pk_bf16_f32 v112, v112, v113
	v_cvt_pk_bf16_f32 v113, v134, v135
	s_and_saveexec_b64 s[52:53], s[6:7]
	s_cbranch_execz .LBB0_585
	s_add_u32 s58, s67, s54
	s_addc_u32 s59, s68, s47
	v_lshl_add_u64 v[114:115], v[192:193], 2, s[58:59]
	v_add_co_u32_e32 v134, vcc, 0x2000, v114
	global_store_dwordx4 v[114:115], v[144:147], off
	s_nop 0
	v_addc_co_u32_e32 v135, vcc, 0, v115, vcc
	v_add_co_u32_e32 v114, vcc, 0x5000, v114
	global_store_dwordx4 v[134:135], v[156:159], off offset:3072
	s_nop 0
	v_addc_co_u32_e32 v115, vcc, 0, v115, vcc
	global_store_dwordx4 v[114:115], v[152:155], off offset:2048
.LBB0_585:
	s_or_b64 exec, exec, s[52:53]
	v_pk_mul_f32 v[100:101], v[100:101], v[164:165] op_sel_hi:[1,0]
	v_pk_mul_f32 v[146:147], v[104:105], v[194:195] op_sel_hi:[1,0]
	v_pk_mul_f32 v[102:103], v[102:103], v[164:165] op_sel_hi:[1,0]
	v_mov_b32_dpp v104, v100 row_shr:1 row_mask:0xf bank_mask:0xf bound_ctrl:1
	v_mov_b32_dpp v105, v101 row_shr:1 row_mask:0xf bank_mask:0xf bound_ctrl:1
	v_pk_mul_f32 v[108:109], v[108:109], v[196:197] op_sel_hi:[1,0]
	v_pk_mul_f32 v[134:135], v[106:107], v[194:195] op_sel_hi:[1,0]
	v_mov_b32_dpp v106, v102 row_shr:1 row_mask:0xf bank_mask:0xf bound_ctrl:1
	v_mov_b32_dpp v107, v103 row_shr:1 row_mask:0xf bank_mask:0xf bound_ctrl:1
	v_pk_mul_f32 v[104:105], v[80:81], v[104:105]
	v_pk_mul_f32 v[110:111], v[110:111], v[196:197] op_sel_hi:[1,0]
	v_pk_mul_f32 v[106:107], v[82:83], v[106:107]
	v_pk_fma_f32 v[104:105], v[84:85], v[108:109], v[104:105]
	v_pk_fma_f32 v[106:107], v[86:87], v[110:111], v[106:107]
	v_pk_fma_f32 v[104:105], v[146:147], v[76:77], v[104:105]
	v_pk_fma_f32 v[106:107], v[134:135], v[78:79], v[106:107]
	v_pk_add_f32 v[104:105], v[72:73], v[104:105]
	v_pk_add_f32 v[106:107], v[74:75], v[106:107]
	v_pk_mul_f32 v[152:153], v[104:105], v[104:105]
	v_mov_b64_e32 v[154:155], s[42:43]
	v_pk_mul_f32 v[138:139], v[106:107], v[106:107]
	v_pk_fma_f32 v[152:153], v[152:153], s[40:41], v[154:155] op_sel_hi:[1,0,0] neg_lo:[1,0,0] neg_hi:[1,0,0]
	v_pk_fma_f32 v[138:139], v[138:139], s[40:41], v[154:155] op_sel_hi:[1,0,0] neg_lo:[1,0,0] neg_hi:[1,0,0]
	v_pk_mul_f32 v[152:153], v[104:105], v[152:153]
	v_pk_mul_f32 v[138:139], v[106:107], v[138:139]
	v_exp_f32_e32 v152, v152
	v_exp_f32_e32 v153, v153
	v_exp_f32_e32 v138, v138
	v_exp_f32_e32 v139, v139
	v_pk_mul_f32 v[98:99], v[98:99], v[196:197] op_sel_hi:[1,0]
	v_pk_add_f32 v[152:153], v[152:153], 1.0 op_sel_hi:[1,0]
	v_pk_mul_f32 v[96:97], v[96:97], v[196:197] op_sel_hi:[1,0]
	v_rcp_f32_e32 v152, v152
	v_pk_add_f32 v[138:139], v[138:139], 1.0 op_sel_hi:[1,0]
	v_rcp_f32_e32 v153, v153
	v_rcp_f32_e32 v138, v138
	v_rcp_f32_e32 v139, v139
	v_mov_b32_dpp v114, v108 row_shl:1 row_mask:0xf bank_mask:0xf bound_ctrl:1
	v_pk_mul_f32 v[150:151], v[104:105], v[152:153]
	v_mov_b32_dpp v115, v109 row_shl:1 row_mask:0xf bank_mask:0xf bound_ctrl:1
	v_mov_b32_dpp v144, v110 row_shl:1 row_mask:0xf bank_mask:0xf bound_ctrl:1
	v_mov_b32_dpp v145, v111 row_shl:1 row_mask:0xf bank_mask:0xf bound_ctrl:1
	v_pk_mul_f32 v[138:139], v[106:107], v[138:139]
	v_pk_mul_f32 v[150:151], v[96:97], v[150:151]
	v_pk_mul_f32 v[138:139], v[98:99], v[138:139]
	v_cvt_pk_bf16_f32 v150, v150, v151
	s_nop 0
	v_cvt_pk_bf16_f32 v151, v138, v139
	s_and_saveexec_b64 s[52:53], s[8:9]
	s_cbranch_execz .LBB0_587
	s_add_u32 s56, s67, s56
	s_addc_u32 s57, s68, s57
	v_lshl_add_u64 v[138:139], v[192:193], 2, s[56:57]
	global_store_dwordx4 v[138:139], v[104:107], off offset:16
	s_nop 1
	v_add_co_u32_e32 v104, vcc, 0x2000, v138
	s_nop 1
	v_addc_co_u32_e32 v105, vcc, 0, v139, vcc
	global_store_dwordx4 v[104:105], v[96:99], off offset:3088
	s_nop 1
	v_add_co_u32_e32 v96, vcc, 0x5000, v138
	s_nop 1
	v_addc_co_u32_e32 v97, vcc, 0, v139, vcc
	global_store_dwordx4 v[96:97], v[108:111], off offset:2064
.LBB0_587:
	s_or_b64 exec, exec, s[52:53]
	v_pk_mul_f32 v[98:99], v[86:87], v[134:135]
	v_pk_mul_f32 v[104:105], v[84:85], v[146:147]
	v_pk_mul_f32 v[94:95], v[94:95], v[166:167] op_sel_hi:[1,0]
	v_pk_mul_f32 v[92:93], v[92:93], v[166:167] op_sel_hi:[1,0]
	v_pk_fma_f32 v[98:99], v[82:83], v[110:111], v[98:99]
	v_pk_fma_f32 v[104:105], v[80:81], v[108:109], v[104:105]
	v_pk_fma_f32 v[98:99], v[94:95], v[78:79], v[98:99]
	v_pk_fma_f32 v[104:105], v[92:93], v[76:77], v[104:105]
	v_pk_add_f32 v[98:99], v[74:75], v[98:99]
	v_pk_add_f32 v[104:105], v[72:73], v[104:105]
	v_pk_mul_f32 v[108:109], v[98:99], v[98:99]
	v_pk_mul_f32 v[110:111], v[104:105], v[104:105]
	v_mov_b64_e32 v[152:153], s[42:43]
	v_pk_fma_f32 v[110:111], v[110:111], s[40:41], v[152:153] op_sel_hi:[1,0,0] neg_lo:[1,0,0] neg_hi:[1,0,0]
	v_pk_fma_f32 v[108:109], v[108:109], s[40:41], v[152:153] op_sel_hi:[1,0,0] neg_lo:[1,0,0] neg_hi:[1,0,0]
	v_pk_mul_f32 v[110:111], v[104:105], v[110:111]
	v_pk_mul_f32 v[108:109], v[98:99], v[108:109]
	v_exp_f32_e32 v110, v110
	v_exp_f32_e32 v111, v111
	v_exp_f32_e32 v108, v108
	v_exp_f32_e32 v109, v109
	v_pk_add_f32 v[110:111], v[110:111], 1.0 op_sel_hi:[1,0]
	v_pk_add_f32 v[108:109], v[108:109], 1.0 op_sel_hi:[1,0]
	v_rcp_f32_e32 v110, v110
	v_rcp_f32_e32 v108, v108
	v_rcp_f32_e32 v109, v109
	v_rcp_f32_e32 v111, v111
	v_pk_mul_f32 v[90:91], v[90:91], v[194:195] op_sel_hi:[1,0]
	v_pk_mul_f32 v[88:89], v[88:89], v[194:195] op_sel_hi:[1,0]
	v_pk_mul_f32 v[98:99], v[98:99], v[108:109]
	v_pk_mul_f32 v[104:105], v[104:105], v[110:111]
	v_pk_mul_f32 v[90:91], v[90:91], v[98:99]
	v_pk_mul_f32 v[88:89], v[88:89], v[104:105]
	v_pk_mul_f32 v[70:71], v[70:71], v[166:167] op_sel_hi:[1,0]
	v_cvt_pk_bf16_f32 v138, v88, v89
	v_cvt_pk_bf16_f32 v139, v90, v91
	v_pk_mul_f32 v[88:89], v[86:87], v[94:95]
	v_pk_mul_f32 v[90:91], v[84:85], v[92:93]
	v_pk_fma_f32 v[88:89], v[82:83], v[134:135], v[88:89]
	v_pk_fma_f32 v[90:91], v[80:81], v[146:147], v[90:91]
	v_pk_fma_f32 v[88:89], v[102:103], v[78:79], v[88:89]
	v_pk_fma_f32 v[90:91], v[100:101], v[76:77], v[90:91]
	v_pk_add_f32 v[88:89], v[74:75], v[88:89]
	v_pk_add_f32 v[90:91], v[72:73], v[90:91]
	v_pk_mul_f32 v[98:99], v[88:89], v[88:89]
	v_pk_mul_f32 v[104:105], v[90:91], v[90:91]
	v_pk_fma_f32 v[98:99], v[98:99], s[40:41], v[152:153] op_sel_hi:[1,0,0] neg_lo:[1,0,0] neg_hi:[1,0,0]
	v_pk_fma_f32 v[104:105], v[104:105], s[40:41], v[152:153] op_sel_hi:[1,0,0] neg_lo:[1,0,0] neg_hi:[1,0,0]
	v_pk_mul_f32 v[98:99], v[88:89], v[98:99]
	v_pk_mul_f32 v[104:105], v[90:91], v[104:105]
	v_exp_f32_e32 v98, v98
	v_exp_f32_e32 v104, v104
	v_exp_f32_e32 v105, v105
	v_exp_f32_e32 v99, v99
	v_pk_mul_f32 v[68:69], v[68:69], v[166:167] op_sel_hi:[1,0]
	v_pk_mul_f32 v[64:65], v[64:65], v[164:165] op_sel_hi:[1,0]
	v_pk_add_f32 v[104:105], v[104:105], 1.0 op_sel_hi:[1,0]
	v_pk_add_f32 v[98:99], v[98:99], 1.0 op_sel_hi:[1,0]
	v_rcp_f32_e32 v104, v104
	v_rcp_f32_e32 v105, v105
	v_rcp_f32_e32 v98, v98
	v_rcp_f32_e32 v99, v99
	v_pk_mul_f32 v[90:91], v[90:91], v[104:105]
	s_nop 0
	v_pk_mul_f32 v[68:69], v[68:69], v[90:91]
	v_pk_mul_f32 v[88:89], v[88:89], v[98:99]
	v_cvt_pk_bf16_f32 v134, v68, v69
	v_pk_mul_f32 v[68:69], v[86:87], v[102:103]
	v_pk_mul_f32 v[70:71], v[70:71], v[88:89]
	v_pk_fma_f32 v[68:69], v[82:83], v[94:95], v[68:69]
	v_cvt_pk_bf16_f32 v135, v70, v71
	v_pk_mul_f32 v[70:71], v[84:85], v[100:101]
	v_pk_fma_f32 v[68:69], v[78:79], v[144:145], v[68:69]
	v_pk_fma_f32 v[70:71], v[80:81], v[92:93], v[70:71]
	s_nop 0
	v_pk_fma_f32 v[88:89], v[76:77], v[114:115], v[70:71]
	v_pk_add_f32 v[70:71], v[74:75], v[68:69]
	v_pk_add_f32 v[68:69], v[72:73], v[88:89]
	v_pk_mul_f32 v[90:91], v[70:71], v[70:71]
	v_pk_mul_f32 v[92:93], v[68:69], v[68:69]
	v_pk_fma_f32 v[90:91], v[90:91], s[40:41], v[152:153] op_sel_hi:[1,0,0] neg_lo:[1,0,0] neg_hi:[1,0,0]
	v_pk_fma_f32 v[92:93], v[92:93], s[40:41], v[152:153] op_sel_hi:[1,0,0] neg_lo:[1,0,0] neg_hi:[1,0,0]
	v_pk_mul_f32 v[90:91], v[70:71], v[90:91]
	v_pk_mul_f32 v[92:93], v[68:69], v[92:93]
	v_exp_f32_e32 v90, v90
	v_exp_f32_e32 v92, v92
	v_exp_f32_e32 v93, v93
	v_exp_f32_e32 v91, v91
	v_pk_add_f32 v[92:93], v[92:93], 1.0 op_sel_hi:[1,0]
	v_pk_add_f32 v[90:91], v[90:91], 1.0 op_sel_hi:[1,0]
	v_rcp_f32_e32 v92, v92
	v_rcp_f32_e32 v90, v90
	v_rcp_f32_e32 v91, v91
	v_rcp_f32_e32 v93, v93
	v_pk_mul_f32 v[66:67], v[66:67], v[164:165] op_sel_hi:[1,0]
	v_pk_mul_f32 v[88:89], v[70:71], v[90:91]
	v_pk_mul_f32 v[90:91], v[68:69], v[92:93]
	v_pk_mul_f32 v[88:89], v[66:67], v[88:89]
	v_pk_mul_f32 v[90:91], v[64:65], v[90:91]
	s_nop 0
	v_cvt_pk_bf16_f32 v114, v90, v91
	v_cvt_pk_bf16_f32 v115, v88, v89
	s_and_saveexec_b64 s[52:53], s[6:7]
	s_cbranch_execz .LBB0_589
	s_add_u32 s56, s67, s54
	s_addc_u32 s57, s68, s47
	v_lshl_add_u64 v[88:89], v[192:193], 2, s[56:57]
	global_store_dwordx4 v[88:89], v[68:71], off offset:16
	s_nop 1
	v_add_co_u32_e32 v68, vcc, 0x2000, v88
	s_nop 1
	v_addc_co_u32_e32 v69, vcc, 0, v89, vcc
	global_store_dwordx4 v[68:69], v[64:67], off offset:3088
	s_nop 1
	v_add_co_u32_e32 v64, vcc, 0x5000, v88
	s_nop 1
	v_addc_co_u32_e32 v65, vcc, 0, v89, vcc
	global_store_dwordx4 v[64:65], v[100:103], off offset:2064

.LBB0_591:
	s_or_b64 exec, exec, s[52:53]
	v_fmamk_f32 v50, v142, 0x3a800000, v210
	v_rsq_f32_e32 v64, v50
	v_pk_mul_f32 v[56:57], v[128:129], v[98:99]
	v_mov_b64_e32 v[66:67], s[42:43]
	v_pk_fma_f32 v[56:57], v[120:121], v[60:61], v[56:57]
	v_pk_mul_f32 v[50:51], v[46:47], v[64:65] op_sel_hi:[1,0]
	v_pk_mul_f32 v[46:47], v[130:131], v[96:97]
	v_pk_mul_f32 v[44:45], v[44:45], v[64:65] op_sel_hi:[1,0]
	v_pk_fma_f32 v[46:47], v[122:123], v[62:63], v[46:47]
	v_pk_fma_f32 v[56:57], v[116:117], v[44:45], v[56:57]
	v_pk_fma_f32 v[46:47], v[118:119], v[50:51], v[46:47]
	v_pk_add_f32 v[56:57], v[124:125], v[56:57]
	v_pk_add_f32 v[58:59], v[126:127], v[46:47]
	v_pk_mul_f32 v[62:63], v[56:57], v[56:57]
	v_pk_mul_f32 v[60:61], v[58:59], v[58:59]
	v_pk_fma_f32 v[62:63], v[62:63], s[40:41], v[66:67] op_sel_hi:[1,0,0] neg_lo:[1,0,0] neg_hi:[1,0,0]
	v_pk_fma_f32 v[60:61], v[60:61], s[40:41], v[66:67] op_sel_hi:[1,0,0] neg_lo:[1,0,0] neg_hi:[1,0,0]
	v_pk_mul_f32 v[62:63], v[56:57], v[62:63]
	v_pk_mul_f32 v[60:61], v[58:59], v[60:61]
	v_exp_f32_e32 v62, v62
	v_exp_f32_e32 v63, v63
	v_exp_f32_e32 v60, v60
	v_exp_f32_e32 v61, v61
	v_pk_add_f32 v[62:63], v[62:63], 1.0 op_sel_hi:[1,0]
	v_pk_add_f32 v[60:61], v[60:61], 1.0 op_sel_hi:[1,0]
	v_rcp_f32_e32 v62, v62
	v_rcp_f32_e32 v60, v60
	v_rcp_f32_e32 v61, v61
	v_rcp_f32_e32 v63, v63
	v_pk_mul_f32 v[42:43], v[42:43], v[88:89] op_sel_hi:[1,0]
	v_pk_mul_f32 v[40:41], v[40:41], v[88:89] op_sel_hi:[1,0]
	v_pk_mul_f32 v[58:59], v[58:59], v[60:61]
	v_pk_mul_f32 v[56:57], v[56:57], v[62:63]
	v_pk_mul_f32 v[42:43], v[42:43], v[58:59]
	v_pk_mul_f32 v[40:41], v[40:41], v[56:57]
	v_pk_mul_f32 v[56:57], v[128:129], v[44:45]
	v_cvt_pk_bf16_f32 v40, v40, v41
	v_cvt_pk_bf16_f32 v41, v42, v43
	v_pk_mul_f32 v[42:43], v[130:131], v[50:51]
	v_pk_fma_f32 v[56:57], v[120:121], v[98:99], v[56:57]
	v_pk_fma_f32 v[42:43], v[122:123], v[96:97], v[42:43]
	v_pk_fma_f32 v[56:57], v[116:117], v[52:53], v[56:57]
	v_pk_fma_f32 v[42:43], v[118:119], v[54:55], v[42:43]
	v_pk_add_f32 v[56:57], v[124:125], v[56:57]
	v_pk_add_f32 v[42:43], v[126:127], v[42:43]
	v_pk_mul_f32 v[60:61], v[56:57], v[56:57]
	v_pk_mul_f32 v[58:59], v[42:43], v[42:43]
	v_pk_fma_f32 v[60:61], v[60:61], s[40:41], v[66:67] op_sel_hi:[1,0,0] neg_lo:[1,0,0] neg_hi:[1,0,0]
	v_pk_fma_f32 v[58:59], v[58:59], s[40:41], v[66:67] op_sel_hi:[1,0,0] neg_lo:[1,0,0] neg_hi:[1,0,0]
	v_pk_mul_f32 v[60:61], v[56:57], v[60:61]
	v_pk_mul_f32 v[58:59], v[42:43], v[58:59]
	v_exp_f32_e32 v60, v60
	v_exp_f32_e32 v61, v61
	v_exp_f32_e32 v58, v58
	v_exp_f32_e32 v59, v59
	v_pk_mul_f32 v[36:37], v[36:37], v[64:65] op_sel_hi:[1,0]
	v_pk_add_f32 v[60:61], v[60:61], 1.0 op_sel_hi:[1,0]
	v_pk_mul_f32 v[38:39], v[38:39], v[64:65] op_sel_hi:[1,0]
	v_pk_add_f32 v[58:59], v[58:59], 1.0 op_sel_hi:[1,0]
	v_rcp_f32_e32 v60, v60
	v_rcp_f32_e32 v61, v61
	v_rcp_f32_e32 v58, v58
	v_rcp_f32_e32 v59, v59
	v_pk_mul_f32 v[56:57], v[56:57], v[60:61]
	s_add_i32 s54, s47, 3
	v_pk_mul_f32 v[42:43], v[42:43], v[58:59]
	v_pk_mul_f32 v[36:37], v[36:37], v[56:57]
	v_pk_mul_f32 v[38:39], v[38:39], v[42:43]
	v_cvt_pk_bf16_f32 v36, v36, v37
	v_pk_mul_f32 v[42:43], v[128:129], v[52:53]
	v_cvt_pk_bf16_f32 v37, v38, v39
	v_pk_mul_f32 v[38:39], v[130:131], v[54:55]
	v_pk_fma_f32 v[42:43], v[120:121], v[44:45], v[42:43]
	v_pk_fma_f32 v[38:39], v[122:123], v[50:51], v[38:39]
	v_pk_fma_f32 v[42:43], v[116:117], v[92:93], v[42:43]
	v_pk_fma_f32 v[38:39], v[118:119], v[94:95], v[38:39]
	v_pk_add_f32 v[42:43], v[124:125], v[42:43]
	v_pk_add_f32 v[44:45], v[126:127], v[38:39]
	v_pk_mul_f32 v[56:57], v[42:43], v[42:43]
	v_pk_mul_f32 v[38:39], v[44:45], v[44:45]
	v_pk_fma_f32 v[56:57], v[56:57], s[40:41], v[66:67] op_sel_hi:[1,0,0] neg_lo:[1,0,0] neg_hi:[1,0,0]
	v_pk_fma_f32 v[38:39], v[38:39], s[40:41], v[66:67] op_sel_hi:[1,0,0] neg_lo:[1,0,0] neg_hi:[1,0,0]
	v_pk_mul_f32 v[56:57], v[42:43], v[56:57]
	v_pk_mul_f32 v[38:39], v[44:45], v[38:39]
	v_exp_f32_e32 v56, v56
	v_exp_f32_e32 v57, v57
	v_exp_f32_e32 v38, v38
	v_exp_f32_e32 v39, v39
	v_pk_add_f32 v[56:57], v[56:57], 1.0 op_sel_hi:[1,0]
	v_pk_add_f32 v[38:39], v[38:39], 1.0 op_sel_hi:[1,0]
	v_rcp_f32_e32 v60, v56
	v_rcp_f32_e32 v38, v38
	v_rcp_f32_e32 v39, v39
	v_rcp_f32_e32 v61, v57
	v_pk_mul_f32 v[58:59], v[34:35], v[70:71] op_sel_hi:[1,0]
	v_pk_mul_f32 v[56:57], v[32:33], v[70:71] op_sel_hi:[1,0]
	v_pk_mul_f32 v[32:33], v[44:45], v[38:39]
	v_pk_mul_f32 v[34:35], v[42:43], v[60:61]
	s_mul_hi_i32 s47, s54, 0x2c00
	s_mulk_i32 s54, 0x2c00
	v_pk_mul_f32 v[38:39], v[58:59], v[32:33]
	v_pk_mul_f32 v[32:33], v[56:57], v[34:35]
	s_nop 0
	v_cvt_pk_bf16_f32 v32, v32, v33
	v_cvt_pk_bf16_f32 v33, v38, v39
	s_and_saveexec_b64 s[52:53], s[6:7]
	s_cbranch_execz .LBB0_593
	s_add_u32 s58, s67, s54
	s_addc_u32 s59, s68, s47
	v_lshl_add_u64 v[34:35], v[192:193], 2, s[58:59]
	v_add_co_u32_e32 v38, vcc, 0x2000, v34
	global_store_dwordx4 v[34:35], v[42:45], off
	s_nop 0
	v_addc_co_u32_e32 v39, vcc, 0, v35, vcc
	v_add_co_u32_e32 v34, vcc, 0x5000, v34
	global_store_dwordx4 v[38:39], v[56:59], off offset:3072
	s_nop 0
	v_addc_co_u32_e32 v35, vcc, 0, v35, vcc
	global_store_dwordx4 v[34:35], v[52:55], off offset:2048
.LBB0_593:
	s_or_b64 exec, exec, s[52:53]
	v_pk_mul_f32 v[22:23], v[22:23], v[70:71] op_sel_hi:[1,0]
	v_pk_mul_f32 v[20:21], v[20:21], v[70:71] op_sel_hi:[1,0]
	v_pk_mul_f32 v[38:39], v[26:27], v[88:89] op_sel_hi:[1,0]
	v_pk_mul_f32 v[46:47], v[24:25], v[88:89] op_sel_hi:[1,0]
	v_mov_b32_dpp v24, v20 row_shr:1 row_mask:0xf bank_mask:0xf bound_ctrl:1
	v_mov_b32_dpp v25, v21 row_shr:1 row_mask:0xf bank_mask:0xf bound_ctrl:1
	v_mov_b32_dpp v26, v22 row_shr:1 row_mask:0xf bank_mask:0xf bound_ctrl:1
	v_mov_b32_dpp v27, v23 row_shr:1 row_mask:0xf bank_mask:0xf bound_ctrl:1
	v_pk_mul_f32 v[30:31], v[30:31], v[90:91] op_sel_hi:[1,0]
	v_pk_mul_f32 v[28:29], v[28:29], v[90:91] op_sel_hi:[1,0]
	v_pk_mul_f32 v[26:27], v[82:83], v[26:27]
	v_pk_mul_f32 v[24:25], v[80:81], v[24:25]
	v_pk_fma_f32 v[26:27], v[86:87], v[30:31], v[26:27]
	v_pk_fma_f32 v[24:25], v[84:85], v[28:29], v[24:25]
	v_pk_fma_f32 v[26:27], v[78:79], v[38:39], v[26:27]
	v_pk_fma_f32 v[24:25], v[76:77], v[46:47], v[24:25]
	v_pk_add_f32 v[26:27], v[74:75], v[26:27]
	v_pk_add_f32 v[24:25], v[72:73], v[24:25]
	v_pk_mul_f32 v[50:51], v[26:27], v[26:27]
	v_pk_mul_f32 v[52:53], v[24:25], v[24:25]
	v_mov_b64_e32 v[54:55], s[42:43]
	v_pk_fma_f32 v[52:53], v[52:53], s[40:41], v[54:55] op_sel_hi:[1,0,0] neg_lo:[1,0,0] neg_hi:[1,0,0]
	v_pk_fma_f32 v[50:51], v[50:51], s[40:41], v[54:55] op_sel_hi:[1,0,0] neg_lo:[1,0,0] neg_hi:[1,0,0]
	v_pk_mul_f32 v[52:53], v[24:25], v[52:53]
	v_pk_mul_f32 v[50:51], v[26:27], v[50:51]
	v_exp_f32_e32 v52, v52
	v_exp_f32_e32 v53, v53
	v_exp_f32_e32 v50, v50
	v_exp_f32_e32 v51, v51
	v_pk_mul_f32 v[18:19], v[18:19], v[90:91] op_sel_hi:[1,0]
	v_pk_add_f32 v[52:53], v[52:53], 1.0 op_sel_hi:[1,0]
	v_pk_mul_f32 v[16:17], v[16:17], v[90:91] op_sel_hi:[1,0]
	v_pk_add_f32 v[50:51], v[50:51], 1.0 op_sel_hi:[1,0]
	v_rcp_f32_e32 v52, v52
	v_rcp_f32_e32 v50, v50
	v_rcp_f32_e32 v51, v51
	v_rcp_f32_e32 v53, v53
	v_mov_b32_dpp v34, v28 row_shl:1 row_mask:0xf bank_mask:0xf bound_ctrl:1
	v_mov_b32_dpp v35, v29 row_shl:1 row_mask:0xf bank_mask:0xf bound_ctrl:1
	v_pk_mul_f32 v[42:43], v[26:27], v[50:51]
	v_pk_mul_f32 v[50:51], v[24:25], v[52:53]
	v_mov_b32_dpp v44, v30 row_shl:1 row_mask:0xf bank_mask:0xf bound_ctrl:1
	v_mov_b32_dpp v45, v31 row_shl:1 row_mask:0xf bank_mask:0xf bound_ctrl:1
	v_pk_mul_f32 v[50:51], v[16:17], v[50:51]
	v_pk_mul_f32 v[42:43], v[18:19], v[42:43]
	v_cvt_pk_bf16_f32 v50, v50, v51
	s_nop 0
	v_cvt_pk_bf16_f32 v51, v42, v43
	s_and_saveexec_b64 s[52:53], s[8:9]
	s_cbranch_execz .LBB0_595
	s_add_u32 s56, s67, s56
	s_addc_u32 s57, s68, s57
	v_lshl_add_u64 v[42:43], v[192:193], 2, s[56:57]
	global_store_dwordx4 v[42:43], v[24:27], off offset:16
	s_nop 1
	v_add_co_u32_e32 v24, vcc, 0x2000, v42
	s_nop 1
	v_addc_co_u32_e32 v25, vcc, 0, v43, vcc
	global_store_dwordx4 v[24:25], v[16:19], off offset:3088
	s_nop 1
	v_add_co_u32_e32 v16, vcc, 0x5000, v42
	s_nop 1
	v_addc_co_u32_e32 v17, vcc, 0, v43, vcc
	global_store_dwordx4 v[16:17], v[28:31], off offset:2064
.LBB0_595:
	s_or_b64 exec, exec, s[52:53]
	v_pk_mul_f32 v[18:19], v[86:87], v[38:39]
	v_pk_mul_f32 v[24:25], v[84:85], v[46:47]
	v_pk_mul_f32 v[14:15], v[14:15], v[64:65] op_sel_hi:[1,0]
	v_pk_mul_f32 v[12:13], v[12:13], v[64:65] op_sel_hi:[1,0]
	v_pk_fma_f32 v[18:19], v[82:83], v[30:31], v[18:19]
	v_pk_fma_f32 v[24:25], v[80:81], v[28:29], v[24:25]
	v_pk_fma_f32 v[18:19], v[78:79], v[14:15], v[18:19]
	v_pk_fma_f32 v[24:25], v[76:77], v[12:13], v[24:25]
	v_pk_add_f32 v[18:19], v[74:75], v[18:19]
	v_pk_add_f32 v[24:25], v[72:73], v[24:25]
	v_pk_mul_f32 v[28:29], v[18:19], v[18:19]
	v_pk_mul_f32 v[30:31], v[24:25], v[24:25]
	v_mov_b64_e32 v[52:53], s[42:43]
	v_pk_fma_f32 v[30:31], v[30:31], s[40:41], v[52:53] op_sel_hi:[1,0,0] neg_lo:[1,0,0] neg_hi:[1,0,0]
	v_pk_fma_f32 v[28:29], v[28:29], s[40:41], v[52:53] op_sel_hi:[1,0,0] neg_lo:[1,0,0] neg_hi:[1,0,0]
	v_pk_mul_f32 v[30:31], v[24:25], v[30:31]
	v_pk_mul_f32 v[28:29], v[18:19], v[28:29]
	v_exp_f32_e32 v30, v30
	v_exp_f32_e32 v31, v31
	v_exp_f32_e32 v28, v28
	v_exp_f32_e32 v29, v29
	v_pk_add_f32 v[30:31], v[30:31], 1.0 op_sel_hi:[1,0]
	v_pk_add_f32 v[28:29], v[28:29], 1.0 op_sel_hi:[1,0]
	v_rcp_f32_e32 v30, v30
	v_rcp_f32_e32 v28, v28
	v_rcp_f32_e32 v29, v29
	v_rcp_f32_e32 v31, v31
	v_pk_mul_f32 v[10:11], v[10:11], v[88:89] op_sel_hi:[1,0]
	v_pk_mul_f32 v[8:9], v[8:9], v[88:89] op_sel_hi:[1,0]
	v_pk_mul_f32 v[18:19], v[18:19], v[28:29]
	v_pk_mul_f32 v[24:25], v[24:25], v[30:31]
	v_pk_mul_f32 v[10:11], v[10:11], v[18:19]
	v_pk_mul_f32 v[8:9], v[8:9], v[24:25]
	v_pk_mul_f32 v[6:7], v[6:7], v[64:65] op_sel_hi:[1,0]
	v_cvt_pk_bf16_f32 v42, v8, v9
	v_cvt_pk_bf16_f32 v43, v10, v11
	v_pk_mul_f32 v[8:9], v[86:87], v[14:15]
	v_pk_mul_f32 v[10:11], v[84:85], v[12:13]
	v_pk_fma_f32 v[8:9], v[82:83], v[38:39], v[8:9]
	v_pk_fma_f32 v[10:11], v[80:81], v[46:47], v[10:11]
	v_pk_fma_f32 v[8:9], v[78:79], v[22:23], v[8:9]
	v_pk_fma_f32 v[10:11], v[76:77], v[20:21], v[10:11]
	v_pk_add_f32 v[8:9], v[74:75], v[8:9]
	v_pk_add_f32 v[10:11], v[72:73], v[10:11]
	v_pk_mul_f32 v[18:19], v[8:9], v[8:9]
	v_pk_mul_f32 v[24:25], v[10:11], v[10:11]
	v_pk_fma_f32 v[18:19], v[18:19], s[40:41], v[52:53] op_sel_hi:[1,0,0] neg_lo:[1,0,0] neg_hi:[1,0,0]
	v_pk_fma_f32 v[24:25], v[24:25], s[40:41], v[52:53] op_sel_hi:[1,0,0] neg_lo:[1,0,0] neg_hi:[1,0,0]
	v_pk_mul_f32 v[18:19], v[8:9], v[18:19]
	v_pk_mul_f32 v[24:25], v[10:11], v[24:25]
	v_exp_f32_e32 v18, v18
	v_exp_f32_e32 v24, v24
	v_exp_f32_e32 v25, v25
	v_exp_f32_e32 v19, v19
	v_pk_mul_f32 v[4:5], v[4:5], v[64:65] op_sel_hi:[1,0]
	v_pk_mul_f32 v[0:1], v[0:1], v[70:71] op_sel_hi:[1,0]
	v_pk_add_f32 v[24:25], v[24:25], 1.0 op_sel_hi:[1,0]
	v_pk_add_f32 v[18:19], v[18:19], 1.0 op_sel_hi:[1,0]
	v_rcp_f32_e32 v24, v24
	v_rcp_f32_e32 v25, v25
	v_rcp_f32_e32 v18, v18
	v_rcp_f32_e32 v19, v19
	v_pk_mul_f32 v[10:11], v[10:11], v[24:25]
	s_nop 0
	v_pk_mul_f32 v[4:5], v[4:5], v[10:11]
	v_pk_mul_f32 v[8:9], v[8:9], v[18:19]
	v_cvt_pk_bf16_f32 v38, v4, v5
	v_pk_mul_f32 v[4:5], v[86:87], v[22:23]
	v_pk_mul_f32 v[6:7], v[6:7], v[8:9]
	v_pk_fma_f32 v[4:5], v[82:83], v[14:15], v[4:5]
	v_cvt_pk_bf16_f32 v39, v6, v7
	v_pk_mul_f32 v[6:7], v[84:85], v[20:21]
	v_pk_fma_f32 v[4:5], v[78:79], v[44:45], v[4:5]
	v_pk_fma_f32 v[6:7], v[80:81], v[12:13], v[6:7]
	s_nop 0
	v_pk_fma_f32 v[8:9], v[76:77], v[34:35], v[6:7]
	v_pk_add_f32 v[6:7], v[74:75], v[4:5]
	v_pk_add_f32 v[4:5], v[72:73], v[8:9]
	v_pk_mul_f32 v[10:11], v[6:7], v[6:7]
	v_pk_mul_f32 v[12:13], v[4:5], v[4:5]
	v_pk_fma_f32 v[10:11], v[10:11], s[40:41], v[52:53] op_sel_hi:[1,0,0] neg_lo:[1,0,0] neg_hi:[1,0,0]
	v_pk_fma_f32 v[12:13], v[12:13], s[40:41], v[52:53] op_sel_hi:[1,0,0] neg_lo:[1,0,0] neg_hi:[1,0,0]
	v_pk_mul_f32 v[10:11], v[6:7], v[10:11]
	v_pk_mul_f32 v[12:13], v[4:5], v[12:13]
	v_exp_f32_e32 v10, v10
	v_exp_f32_e32 v12, v12
	v_exp_f32_e32 v13, v13
	v_exp_f32_e32 v11, v11
	v_pk_add_f32 v[12:13], v[12:13], 1.0 op_sel_hi:[1,0]
	v_pk_add_f32 v[10:11], v[10:11], 1.0 op_sel_hi:[1,0]
	v_rcp_f32_e32 v12, v12
	v_rcp_f32_e32 v10, v10
	v_rcp_f32_e32 v11, v11
	v_rcp_f32_e32 v13, v13
	v_pk_mul_f32 v[2:3], v[2:3], v[70:71] op_sel_hi:[1,0]
	v_pk_mul_f32 v[8:9], v[6:7], v[10:11]
	v_pk_mul_f32 v[10:11], v[4:5], v[12:13]
	v_pk_mul_f32 v[8:9], v[2:3], v[8:9]
	v_pk_mul_f32 v[10:11], v[0:1], v[10:11]
	s_nop 0
	v_cvt_pk_bf16_f32 v34, v10, v11
	v_cvt_pk_bf16_f32 v35, v8, v9
	s_and_saveexec_b64 s[52:53], s[6:7]
	s_cbranch_execz .LBB0_597
	s_add_u32 s56, s67, s54
	s_addc_u32 s57, s68, s47
	v_lshl_add_u64 v[8:9], v[192:193], 2, s[56:57]
	global_store_dwordx4 v[8:9], v[4:7], off offset:16
	s_nop 1
	v_add_co_u32_e32 v4, vcc, 0x2000, v8
	s_nop 1
	v_addc_co_u32_e32 v5, vcc, 0, v9, vcc
	global_store_dwordx4 v[4:5], v[0:3], off offset:3088
	s_nop 1
	v_add_co_u32_e32 v0, vcc, 0x5000, v8
	s_nop 1
	v_addc_co_u32_e32 v1, vcc, 0, v9, vcc
	global_store_dwordx4 v[0:1], v[20:23], off offset:2064
